# v037 + zq/zkv/channel-DFT GEMM tiles of phases 3 and 13 re-dealt over the workgroups so none carries all three kinds
# speedup vs baseline: 1.0090x; 1.0090x over previous
.LBB0_329:
	s_abs_i32 s15, s13
	v_cvt_f32_u32_e32 v0, s15
	s_sub_i32 s8, 0, s15
	s_add_i32 s0, s14, 64
	s_ashr_i32 s1, s0, 31
	v_rcp_iflag_f32_e32 v0, v0
	s_abs_i32 s0, s0
	v_mov_b32_e32 v4, v136
	v_mul_f32_e32 v0, 0x4f7ffffe, v0
	v_cvt_u32_f32_e32 v0, v0
	s_nop 0
	v_readfirstlane_b32 s16, v0
	s_mul_i32 s8, s8, s16
	s_mul_hi_u32 s8, s16, s8
	s_add_i32 s16, s16, s8
	s_mul_hi_u32 s8, s0, s16
	s_mul_i32 s8, s8, s15
	s_sub_i32 s0, s0, s8
	s_sub_i32 s8, s0, s15
	s_cmp_ge_u32 s0, s15
	s_cselect_b32 s0, s8, s0
	s_sub_i32 s8, s0, s15
	s_cmp_ge_u32 s0, s15
	s_cselect_b32 s0, s8, s0
	s_xor_b32 s0, s0, s1
	s_sub_i32 s0, s0, s1
	s_mov_b32 s89, s13
	s_cmp_lg_u32 s13, 0x100
	s_cbranch_scc1 .Lrb_zkv_l0
	s_sub_i32 s0, s88, 84
	s_movk_i32 s89, 172
.Lrb_zkv_l0:
	s_cmpk_gt_u32 s0, 0x10f
	v_readfirstlane_b32 s1, v4
	s_cbranch_scc1 .LBB0_343
	v_bfe_i32 v1, v4, 27, 1
	v_lshlrev_b32_e32 v0, 4, v4
	v_lshrrev_b32_e32 v1, 22, v1
	v_add_u32_e32 v1, v0, v1
	v_and_b32_e32 v1, 0xfffffc00, v1
	v_sub_u32_e32 v0, v0, v1
	v_ashrrev_i32_e32 v2, 31, v4
	s_add_u32 s17, s4, 0xac33e00
	v_lshrrev_b32_e32 v1, 4, v0
	v_lshrrev_b32_e32 v2, 26, v2
	s_addc_u32 s20, s5, 0
	v_bitop3_b32 v1, v1, v0, 32 bitop3:0x6c
	v_ashrrev_i32_e32 v0, 31, v0
	v_add_u32_e32 v2, v4, v2
	s_add_u32 s21, s4, 0x25cb600
	v_lshrrev_b32_e32 v0, 26, v0
	v_ashrrev_i32_e32 v2, 6, v2
	s_addc_u32 s28, s5, 0
	v_add_u32_e32 v0, v1, v0
	v_lshlrev_b32_e32 v3, 3, v2
	s_and_b32 s9, s0, 7
	v_ashrrev_i32_e32 v0, 6, v0
	v_and_b32_e32 v3, -16, v3
	s_lshr_b32 s10, s0, 3
	s_mul_i32 s9, s9, 34
	v_add_u32_e32 v3, v0, v3
	v_and_b32_e32 v5, 3, v0
	v_mul_i32_i24_e32 v0, 64, v0
	s_add_i32 s9, s9, s10
	v_lshlrev_b32_e32 v2, 5, v2
	v_sub_u32_e32 v0, v1, v0
	v_mov_b32_e32 v1, 1
	s_lshr_b32 s10, s9, 3
	s_mov_b32 s8, 0x7fffe0
	v_lshrrev_b32_e32 v6, 2, v3
	v_lshlrev_b32_e32 v7, 1, v3
	v_and_b32_e32 v2, 32, v2
	v_ashrrev_i16_sdwa v0, v1, sext(v0) dst_sel:DWORD dst_unused:UNUSED_PAD src0_sel:DWORD src1_sel:BYTE_0
	s_and_b32 s10, s10, 56
	v_and_or_b32 v5, v3, s8, v5
	v_and_b32_e32 v6, 4, v6
	v_and_b32_e32 v7, 24, v7
	v_add_u32_sdwa v0, v2, sext(v0) dst_sel:DWORD dst_unused:UNUSED_PAD src0_sel:DWORD src1_sel:WORD_0
	s_sub_i32 s11, 34, s10
	v_or3_b32 v5, v5, v6, v7
	v_lshlrev_b32_e32 v1, 1, v0
	s_min_u32 s11, s11, 8
	v_lshl_add_u32 v128, v5, 9, v1
	v_cvt_f32_ubyte0_e32 v1, s11
	v_rcp_iflag_f32_e32 v2, v1
	s_and_b32 s18, s9, 63
	v_cvt_f32_ubyte0_e32 v5, s18
	s_movk_i32 s8, 0x2400
	v_mul_f32_e32 v2, v5, v2
	v_trunc_f32_e32 v2, v2
	v_cvt_u32_f32_e32 v6, v2
	v_mul_lo_u32 v3, v3, s8
	s_ashr_i32 s34, s1, 6
	v_add_lshl_u32 v130, v0, v3, 1
	v_fma_f32 v0, -v2, v1, v5
	s_ashr_i32 s29, s1, 8
	s_lshl_b32 s30, s34, 10
	v_cmp_ge_f32_e64 s[8:9], |v0|, v1
	v_readfirstlane_b32 s19, v6
	s_cmp_lg_u64 s[8:9], 0
	s_addc_u32 s8, s19, 0
	s_mul_i32 s9, s8, s11
	s_sub_i32 s9, s18, s9
	s_and_b32 s9, s9, 0xff
	s_add_i32 s44, s10, s9
	s_mul_i32 s9, s44, 0x480000
	s_add_u32 s66, s17, s9
	s_addc_u32 s67, s20, 0
	s_and_b32 s45, s8, 0xff
	s_lshl_b32 s8, s45, 17
	s_add_u32 s68, s21, s8
	s_addc_u32 s69, s28, 0
	v_mov_b32_e32 v129, 0
	s_add_i32 s31, s30, 0
	v_lshl_add_u64 v[0:1], s[68:69], 0, v[128:129]
	s_add_i32 m0, s31, 0x10000
	s_mov_b64 s[8:9], 0x8000
	global_load_lds_dwordx4 v128, s[68:69]
	v_lshl_add_u64 v[2:3], v[0:1], 0, s[8:9]
	s_add_i32 m0, s31, 0x12000
	v_mov_b32_e32 v131, v129
	global_load_lds_dwordx4 v[2:3], off
	v_lshl_add_u64 v[2:3], s[66:67], 0, v[130:131]
	s_mov_b32 m0, s31
	s_mov_b64 s[10:11], 0x120000
	s_add_i32 s33, s31, 0x2000
	global_load_lds_dwordx4 v130, s[66:67]
	v_lshl_add_u64 v[6:7], v[2:3], 0, s[10:11]
	s_mov_b32 m0, s33
	s_mov_b64 s[18:19], 0x10000
	global_load_lds_dwordx4 v[6:7], off
	v_lshl_add_u64 v[6:7], v[0:1], 0, s[18:19]
	s_add_i32 m0, s31, 0x14000
	s_mov_b64 s[22:23], 0x18000
	global_load_lds_dwordx4 v[6:7], off
	v_lshl_add_u64 v[6:7], v[0:1], 0, s[22:23]
	s_add_i32 m0, s31, 0x16000
	s_mov_b64 s[24:25], 0x240000
	s_add_i32 s36, s31, 0x4000
	global_load_lds_dwordx4 v[6:7], off
	v_lshl_add_u64 v[6:7], v[2:3], 0, s[24:25]
	s_mov_b32 m0, s36
	s_mov_b64 s[26:27], 0x360000
	s_add_i32 s37, s31, 0x6000
	global_load_lds_dwordx4 v[6:7], off
	v_lshl_add_u64 v[6:7], v[2:3], 0, s[26:27]
	s_mov_b32 m0, s37
	s_cmp_lg_u32 s29, 1
	global_load_lds_dwordx4 v[6:7], off
	s_mov_b32 s38, 0
	s_cbranch_scc1 .LBB0_332
	s_barrier

.LBB0_334:
	s_add_i32 s38, s38, 1
	s_mul_i32 s46, s38, s89
	s_add_i32 s46, s46, s0
	s_cmpk_lt_i32 s46, 0x110
	s_mov_b64 s[70:71], 0
	s_cselect_b64 s[64:65], -1, 0
	s_cmpk_gt_i32 s46, 0x10f
	s_mov_b64 s[72:73], 0
	s_mov_b64 s[62:63], 0
	s_cbranch_scc1 .LBB0_336
	s_ashr_i32 s47, s46, 31
	s_lshr_b32 s47, s47, 29
	s_add_i32 s47, s46, s47
	s_ashr_i32 s48, s47, 3
	s_and_b32 s47, s47, -8
	s_sub_i32 s46, s46, s47
	s_cmp_lt_i32 s46, 0
	s_cselect_b32 s47, 35, 34
	s_mul_i32 s46, s47, s46
	s_add_i32 s46, s46, s48
	s_ashr_i32 s47, s46, 31
	s_lshr_b32 s47, s47, 26
	s_add_i32 s47, s46, s47
	s_ashr_i32 s48, s47, 6
	s_lshl_b32 s48, s48, 3
	s_sub_i32 s49, 34, s48
	s_min_u32 s49, s49, 8
	s_andn2_b32 s47, s47, 63
	s_sub_i32 s50, s46, s47
	v_cvt_f32_ubyte0_e32 v1, s49
	v_cvt_f32_i32_e32 v0, s50
	v_rcp_iflag_f32_e32 v2, v1
	s_ashr_i32 s46, s50, 30
	s_or_b32 s51, s46, 1
	v_mul_f32_e32 v2, v0, v2
	v_trunc_f32_e32 v2, v2
	v_fma_f32 v0, -v2, v1, v0
	v_cvt_i32_f32_e32 v2, v2
	v_cmp_ge_f32_e64 s[46:47], |v0|, v1
	s_and_b64 s[46:47], s[46:47], exec
	s_cselect_b32 s46, s51, 0
	v_readfirstlane_b32 s47, v2
	s_add_i32 s46, s47, s46
	s_mul_i32 s47, s46, s49
	s_sub_i32 s47, s50, s47
	s_sext_i32_i8 s47, s47
	s_add_i32 s47, s48, s47
	s_mul_hi_i32 s63, s47, 0x480000
	s_mul_i32 s62, s47, 0x480000
	s_bfe_i64 s[46:47], s[46:47], 0x80000
	s_lshl_b64 s[72:73], s[46:47], 17

.LBB0_337:
	s_add_u32 s74, s66, s46
	s_addc_u32 s75, s67, 0
	s_add_u32 s47, s74, 0x100
	s_addc_u32 s50, s75, 0
	s_and_b64 s[48:49], s[70:71], exec
	v_cndmask_b32_e64 v132, 0, 1, s[72:73]
	s_cselect_b32 s72, s62, s47
	s_cselect_b32 s73, s63, s50
	s_add_u32 s46, s68, s46
	s_addc_u32 s47, s69, 0
	ds_read_b128 v[140:143], v135
	ds_read_b128 v[144:147], v135 offset:1024
	ds_read_b128 v[148:151], v135 offset:2048
	ds_read_b128 v[152:155], v135 offset:3072
	s_add_u32 s48, s46, 0x100
	s_addc_u32 s49, s47, 0
	s_and_b64 s[46:47], s[70:71], exec
	s_cselect_b32 s70, s64, s48
	s_cselect_b32 s71, s65, s49
	s_add_i32 s49, 0, 0x1c000
	s_add_i32 s51, 0, 0x18000
	s_add_i32 s47, s49, s30
	s_add_i32 s79, s42, s30
	s_add_i32 s77, s43, s30
	s_add_i32 s50, s51, s30
	s_add_i32 s46, s47, 0x2000
	s_add_i32 m0, s31, 0xc000
	s_add_i32 s80, s31, 0xe000
	s_add_i32 s78, s79, 0x2000
	s_add_i32 s76, s77, 0x2000
	s_add_i32 s48, s50, 0x2000
	v_cmp_ne_u32_e32 vcc, 1, v132
	v_lshl_add_u64 v[132:133], s[74:75], 0, v[130:131]
	s_mov_b64 s[74:75], 0x240080
	v_lshl_add_u64 v[188:189], v[132:133], 0, s[74:75]
	s_mov_b64 s[74:75], 0x360080
	ds_read_b128 v[156:159], v137
	ds_read_b128 v[160:163], v137 offset:1024
	ds_read_b128 v[164:167], v137 offset:2048
	ds_read_b128 v[168:171], v137 offset:3072
	ds_read_b128 v[172:175], v137 offset:4096
	ds_read_b128 v[176:179], v137 offset:5120
	ds_read_b128 v[180:183], v137 offset:6144
	ds_read_b128 v[184:187], v137 offset:7168
	global_load_lds_dwordx4 v[188:189], off
	v_lshl_add_u64 v[132:133], v[132:133], 0, s[74:75]
	s_mov_b32 m0, s80
	s_nop 0
	global_load_lds_dwordx4 v[132:133], off
	s_waitcnt lgkmcnt(8)
	s_barrier
	s_waitcnt lgkmcnt(0)
	s_waitcnt lgkmcnt(0)
	v_mfma_f32_16x16x32_bf16 v[124:127], v[140:143], v[156:159], v[124:127]
	v_mfma_f32_16x16x32_bf16 v[120:123], v[148:151], v[156:159], v[120:123]
	v_mfma_f32_16x16x32_bf16 v[112:115], v[140:143], v[164:167], v[112:115]
	v_mfma_f32_16x16x32_bf16 v[104:107], v[148:151], v[164:167], v[104:107]
	v_mfma_f32_16x16x32_bf16 v[96:99], v[140:143], v[172:175], v[96:99]
	v_mfma_f32_16x16x32_bf16 v[88:91], v[148:151], v[172:175], v[88:91]
	v_mfma_f32_16x16x32_bf16 v[80:83], v[140:143], v[180:183], v[80:83]
	v_mfma_f32_16x16x32_bf16 v[72:75], v[148:151], v[180:183], v[72:75]
	v_mfma_f32_16x16x32_bf16 v[124:127], v[144:147], v[160:163], v[124:127]
	v_mfma_f32_16x16x32_bf16 v[120:123], v[152:155], v[160:163], v[120:123]
	v_mfma_f32_16x16x32_bf16 v[112:115], v[144:147], v[168:171], v[112:115]
	v_mfma_f32_16x16x32_bf16 v[104:107], v[152:155], v[168:171], v[104:107]
	v_mfma_f32_16x16x32_bf16 v[96:99], v[144:147], v[176:179], v[96:99]
	v_mfma_f32_16x16x32_bf16 v[88:91], v[152:155], v[176:179], v[88:91]
	v_mfma_f32_16x16x32_bf16 v[80:83], v[144:147], v[184:187], v[80:83]
	v_mfma_f32_16x16x32_bf16 v[72:75], v[152:155], v[184:187], v[72:75]
	s_barrier
	s_mov_b32 m0, s79
	v_lshl_add_u64 v[132:133], s[70:71], 0, v[128:129]
	ds_read_b128 v[188:191], v138
	ds_read_b128 v[192:195], v138 offset:1024
	ds_read_b128 v[196:199], v138 offset:2048
	ds_read_b128 v[200:203], v138 offset:3072
	global_load_lds_dwordx4 v[132:133], off
	v_lshl_add_u64 v[204:205], v[132:133], 0, s[8:9]
	s_mov_b32 m0, s78
	s_nop 0
	global_load_lds_dwordx4 v[204:205], off
	s_barrier
	s_waitcnt lgkmcnt(0)
	s_waitcnt lgkmcnt(0)
	v_mfma_f32_16x16x32_bf16 v[116:119], v[188:191], v[156:159], v[116:119]
	v_mfma_f32_16x16x32_bf16 v[108:111], v[196:199], v[156:159], v[108:111]
	v_mfma_f32_16x16x32_bf16 v[100:103], v[188:191], v[164:167], v[100:103]
	v_mfma_f32_16x16x32_bf16 v[92:95], v[196:199], v[164:167], v[92:95]
	v_mfma_f32_16x16x32_bf16 v[84:87], v[188:191], v[172:175], v[84:87]
	v_mfma_f32_16x16x32_bf16 v[76:79], v[196:199], v[172:175], v[76:79]
	v_mfma_f32_16x16x32_bf16 v[68:71], v[188:191], v[180:183], v[68:71]
	v_mfma_f32_16x16x32_bf16 v[64:67], v[196:199], v[180:183], v[64:67]
	v_mfma_f32_16x16x32_bf16 v[116:119], v[192:195], v[160:163], v[116:119]
	v_mfma_f32_16x16x32_bf16 v[108:111], v[200:203], v[160:163], v[108:111]
	v_mfma_f32_16x16x32_bf16 v[100:103], v[192:195], v[168:171], v[100:103]
	v_mfma_f32_16x16x32_bf16 v[92:95], v[200:203], v[168:171], v[92:95]
	v_mfma_f32_16x16x32_bf16 v[84:87], v[192:195], v[176:179], v[84:87]
	v_mfma_f32_16x16x32_bf16 v[76:79], v[200:203], v[176:179], v[76:79]
	v_mfma_f32_16x16x32_bf16 v[68:71], v[192:195], v[184:187], v[68:71]
	v_mfma_f32_16x16x32_bf16 v[64:67], v[200:203], v[184:187], v[64:67]
	s_mov_b32 m0, s31
	v_lshl_add_u64 v[204:205], s[72:73], 0, v[130:131]
	s_barrier
	ds_read_b128 v[156:159], v137 offset:16384
	ds_read_b128 v[160:163], v137 offset:17408
	ds_read_b128 v[164:167], v137 offset:18432
	ds_read_b128 v[168:171], v137 offset:19456
	ds_read_b128 v[172:175], v137 offset:20480
	ds_read_b128 v[176:179], v137 offset:21504
	ds_read_b128 v[180:183], v137 offset:22528
	ds_read_b128 v[184:187], v137 offset:23552
	global_load_lds_dwordx4 v[204:205], off
	v_lshl_add_u64 v[206:207], v[204:205], 0, s[10:11]
	s_mov_b32 m0, s33
	s_nop 0
	global_load_lds_dwordx4 v[206:207], off
	s_barrier
	s_waitcnt lgkmcnt(0)
	s_waitcnt lgkmcnt(0)
	v_mfma_f32_16x16x32_bf16 v[60:63], v[140:143], v[156:159], v[60:63]
	v_mfma_f32_16x16x32_bf16 v[56:59], v[148:151], v[156:159], v[56:59]
	v_mfma_f32_16x16x32_bf16 v[48:51], v[140:143], v[164:167], v[48:51]
	v_mfma_f32_16x16x32_bf16 v[40:43], v[148:151], v[164:167], v[40:43]
	v_mfma_f32_16x16x32_bf16 v[32:35], v[140:143], v[172:175], v[32:35]
	v_mfma_f32_16x16x32_bf16 v[24:27], v[148:151], v[172:175], v[24:27]
	v_mfma_f32_16x16x32_bf16 v[16:19], v[140:143], v[180:183], v[16:19]
	v_mfma_f32_16x16x32_bf16 v[8:11], v[148:151], v[180:183], v[8:11]
	v_mfma_f32_16x16x32_bf16 v[60:63], v[144:147], v[160:163], v[60:63]
	v_mfma_f32_16x16x32_bf16 v[56:59], v[152:155], v[160:163], v[56:59]
	v_mfma_f32_16x16x32_bf16 v[48:51], v[144:147], v[168:171], v[48:51]
	v_mfma_f32_16x16x32_bf16 v[40:43], v[152:155], v[168:171], v[40:43]
	v_mfma_f32_16x16x32_bf16 v[32:35], v[144:147], v[176:179], v[32:35]
	v_mfma_f32_16x16x32_bf16 v[24:27], v[152:155], v[176:179], v[24:27]
	v_mfma_f32_16x16x32_bf16 v[16:19], v[144:147], v[184:187], v[16:19]
	v_mfma_f32_16x16x32_bf16 v[8:11], v[152:155], v[184:187], v[8:11]
	s_barrier
	s_mov_b32 m0, s77
	v_lshl_add_u64 v[140:141], v[132:133], 0, s[18:19]
	global_load_lds_dwordx4 v[140:141], off
	v_lshl_add_u64 v[140:141], v[132:133], 0, s[22:23]
	s_mov_b32 m0, s76
	s_nop 0
	global_load_lds_dwordx4 v[140:141], off
	s_waitcnt vmcnt(6)
	s_barrier
	v_mfma_f32_16x16x32_bf16 v[52:55], v[188:191], v[156:159], v[52:55]
	v_mfma_f32_16x16x32_bf16 v[44:47], v[196:199], v[156:159], v[44:47]
	v_mfma_f32_16x16x32_bf16 v[36:39], v[188:191], v[164:167], v[36:39]
	v_mfma_f32_16x16x32_bf16 v[28:31], v[196:199], v[164:167], v[28:31]
	v_mfma_f32_16x16x32_bf16 v[20:23], v[188:191], v[172:175], v[20:23]
	v_mfma_f32_16x16x32_bf16 v[12:15], v[196:199], v[172:175], v[12:15]
	v_mfma_f32_16x16x32_bf16 v[4:7], v[188:191], v[180:183], v[4:7]
	v_mfma_f32_16x16x32_bf16 v[0:3], v[196:199], v[180:183], v[0:3]
	v_mfma_f32_16x16x32_bf16 v[52:55], v[192:195], v[160:163], v[52:55]
	v_mfma_f32_16x16x32_bf16 v[44:47], v[200:203], v[160:163], v[44:47]
	v_mfma_f32_16x16x32_bf16 v[36:39], v[192:195], v[168:171], v[36:39]
	v_mfma_f32_16x16x32_bf16 v[28:31], v[200:203], v[168:171], v[28:31]
	v_mfma_f32_16x16x32_bf16 v[20:23], v[192:195], v[176:179], v[20:23]
	v_mfma_f32_16x16x32_bf16 v[12:15], v[200:203], v[176:179], v[12:15]
	v_mfma_f32_16x16x32_bf16 v[4:7], v[192:195], v[184:187], v[4:7]
	v_mfma_f32_16x16x32_bf16 v[0:3], v[200:203], v[184:187], v[0:3]
	v_add_u32_e32 v139, s51, v134
	s_barrier
	ds_read_b128 v[140:143], v139
	ds_read_b128 v[144:147], v139 offset:1024
	ds_read_b128 v[148:151], v139 offset:2048
	ds_read_b128 v[152:155], v139 offset:3072
	s_mov_b32 m0, s36
	v_lshl_add_u64 v[188:189], v[204:205], 0, s[24:25]
	ds_read_b128 v[156:159], v137 offset:32768
	ds_read_b128 v[160:163], v137 offset:33792
	ds_read_b128 v[164:167], v137 offset:34816
	ds_read_b128 v[168:171], v137 offset:35840
	ds_read_b128 v[172:175], v137 offset:36864
	ds_read_b128 v[176:179], v137 offset:37888
	ds_read_b128 v[180:183], v137 offset:38912
	ds_read_b128 v[184:187], v137 offset:39936
	global_load_lds_dwordx4 v[188:189], off
	v_lshl_add_u64 v[188:189], v[204:205], 0, s[26:27]
	s_mov_b32 m0, s37
	s_nop 0
	global_load_lds_dwordx4 v[188:189], off
	s_waitcnt lgkmcnt(8)
	s_barrier
	s_waitcnt lgkmcnt(0)
	s_waitcnt lgkmcnt(0)
	v_mfma_f32_16x16x32_bf16 v[124:127], v[140:143], v[156:159], v[124:127]
	v_mfma_f32_16x16x32_bf16 v[120:123], v[148:151], v[156:159], v[120:123]
	v_mfma_f32_16x16x32_bf16 v[112:115], v[140:143], v[164:167], v[112:115]
	v_mfma_f32_16x16x32_bf16 v[104:107], v[148:151], v[164:167], v[104:107]
	v_mfma_f32_16x16x32_bf16 v[96:99], v[140:143], v[172:175], v[96:99]
	v_mfma_f32_16x16x32_bf16 v[88:91], v[148:151], v[172:175], v[88:91]
	v_mfma_f32_16x16x32_bf16 v[80:83], v[140:143], v[180:183], v[80:83]
	v_mfma_f32_16x16x32_bf16 v[72:75], v[148:151], v[180:183], v[72:75]
	v_mfma_f32_16x16x32_bf16 v[124:127], v[144:147], v[160:163], v[124:127]
	v_mfma_f32_16x16x32_bf16 v[120:123], v[152:155], v[160:163], v[120:123]
	v_mfma_f32_16x16x32_bf16 v[112:115], v[144:147], v[168:171], v[112:115]
	v_mfma_f32_16x16x32_bf16 v[104:107], v[152:155], v[168:171], v[104:107]
	v_mfma_f32_16x16x32_bf16 v[96:99], v[144:147], v[176:179], v[96:99]
	v_mfma_f32_16x16x32_bf16 v[88:91], v[152:155], v[176:179], v[88:91]
	v_mfma_f32_16x16x32_bf16 v[80:83], v[144:147], v[184:187], v[80:83]
	v_mfma_f32_16x16x32_bf16 v[72:75], v[152:155], v[184:187], v[72:75]
	s_barrier
	s_mov_b32 m0, s50
	v_add_u32_e32 v139, s49, v134
	v_lshl_add_u64 v[206:207], v[132:133], 0, s[52:53]
	ds_read_b128 v[188:191], v139
	ds_read_b128 v[192:195], v139 offset:1024
	ds_read_b128 v[196:199], v139 offset:2048
	ds_read_b128 v[200:203], v139 offset:3072
	global_load_lds_dwordx4 v[206:207], off
	v_lshl_add_u64 v[206:207], v[132:133], 0, s[54:55]
	s_mov_b32 m0, s48
	s_nop 0
	global_load_lds_dwordx4 v[206:207], off
	s_barrier
	s_waitcnt lgkmcnt(0)
	s_waitcnt lgkmcnt(0)
	v_mfma_f32_16x16x32_bf16 v[116:119], v[188:191], v[156:159], v[116:119]
	v_mfma_f32_16x16x32_bf16 v[108:111], v[196:199], v[156:159], v[108:111]
	v_mfma_f32_16x16x32_bf16 v[100:103], v[188:191], v[164:167], v[100:103]
	v_mfma_f32_16x16x32_bf16 v[92:95], v[196:199], v[164:167], v[92:95]
	v_mfma_f32_16x16x32_bf16 v[84:87], v[188:191], v[172:175], v[84:87]
	v_mfma_f32_16x16x32_bf16 v[76:79], v[196:199], v[172:175], v[76:79]
	v_mfma_f32_16x16x32_bf16 v[68:71], v[188:191], v[180:183], v[68:71]
	v_mfma_f32_16x16x32_bf16 v[64:67], v[196:199], v[180:183], v[64:67]
	v_mfma_f32_16x16x32_bf16 v[116:119], v[192:195], v[160:163], v[116:119]
	v_mfma_f32_16x16x32_bf16 v[108:111], v[200:203], v[160:163], v[108:111]
	v_mfma_f32_16x16x32_bf16 v[100:103], v[192:195], v[168:171], v[100:103]
	v_mfma_f32_16x16x32_bf16 v[92:95], v[200:203], v[168:171], v[92:95]
	v_mfma_f32_16x16x32_bf16 v[84:87], v[192:195], v[176:179], v[84:87]
	v_mfma_f32_16x16x32_bf16 v[76:79], v[200:203], v[176:179], v[76:79]
	v_mfma_f32_16x16x32_bf16 v[68:71], v[192:195], v[184:187], v[68:71]
	v_mfma_f32_16x16x32_bf16 v[64:67], v[200:203], v[184:187], v[64:67]
	s_mov_b32 m0, s40
	v_lshl_add_u64 v[206:207], v[204:205], 0, s[52:53]
	s_barrier
	ds_read_b128 v[156:159], v137 offset:49152
	ds_read_b128 v[160:163], v137 offset:50176
	ds_read_b128 v[164:167], v137 offset:51200
	ds_read_b128 v[168:171], v137 offset:52224
	ds_read_b128 v[172:175], v137 offset:53248
	ds_read_b128 v[176:179], v137 offset:54272
	ds_read_b128 v[180:183], v137 offset:55296
	ds_read_b128 v[184:187], v137 offset:56320
	global_load_lds_dwordx4 v[206:207], off
	v_lshl_add_u64 v[204:205], v[204:205], 0, s[56:57]
	s_mov_b32 m0, s41
	s_nop 0
	global_load_lds_dwordx4 v[204:205], off
	s_barrier
	s_waitcnt lgkmcnt(0)
	s_waitcnt lgkmcnt(0)
	v_mfma_f32_16x16x32_bf16 v[60:63], v[140:143], v[156:159], v[60:63]
	v_mfma_f32_16x16x32_bf16 v[56:59], v[148:151], v[156:159], v[56:59]
	v_mfma_f32_16x16x32_bf16 v[48:51], v[140:143], v[164:167], v[48:51]
	v_mfma_f32_16x16x32_bf16 v[40:43], v[148:151], v[164:167], v[40:43]
	v_mfma_f32_16x16x32_bf16 v[32:35], v[140:143], v[172:175], v[32:35]
	v_mfma_f32_16x16x32_bf16 v[24:27], v[148:151], v[172:175], v[24:27]
	v_mfma_f32_16x16x32_bf16 v[16:19], v[140:143], v[180:183], v[16:19]
	v_mfma_f32_16x16x32_bf16 v[8:11], v[148:151], v[180:183], v[8:11]
	v_mfma_f32_16x16x32_bf16 v[60:63], v[144:147], v[160:163], v[60:63]
	v_mfma_f32_16x16x32_bf16 v[56:59], v[152:155], v[160:163], v[56:59]
	v_mfma_f32_16x16x32_bf16 v[48:51], v[144:147], v[168:171], v[48:51]
	v_mfma_f32_16x16x32_bf16 v[40:43], v[152:155], v[168:171], v[40:43]
	v_mfma_f32_16x16x32_bf16 v[32:35], v[144:147], v[176:179], v[32:35]
	v_mfma_f32_16x16x32_bf16 v[24:27], v[152:155], v[176:179], v[24:27]
	v_mfma_f32_16x16x32_bf16 v[16:19], v[144:147], v[184:187], v[16:19]
	v_mfma_f32_16x16x32_bf16 v[8:11], v[152:155], v[184:187], v[8:11]
	s_barrier
	s_mov_b32 m0, s47
	v_lshl_add_u64 v[140:141], v[132:133], 0, s[58:59]
	global_load_lds_dwordx4 v[140:141], off
	v_lshl_add_u64 v[132:133], v[132:133], 0, s[60:61]
	s_mov_b32 m0, s46
	s_nop 0
	global_load_lds_dwordx4 v[132:133], off
	s_waitcnt vmcnt(6)
	s_barrier
	v_mfma_f32_16x16x32_bf16 v[52:55], v[188:191], v[156:159], v[52:55]
	v_mfma_f32_16x16x32_bf16 v[44:47], v[196:199], v[156:159], v[44:47]
	v_mfma_f32_16x16x32_bf16 v[36:39], v[188:191], v[164:167], v[36:39]
	v_mfma_f32_16x16x32_bf16 v[28:31], v[196:199], v[164:167], v[28:31]
	v_mfma_f32_16x16x32_bf16 v[20:23], v[188:191], v[172:175], v[20:23]
	v_mfma_f32_16x16x32_bf16 v[12:15], v[196:199], v[172:175], v[12:15]
	v_mfma_f32_16x16x32_bf16 v[4:7], v[188:191], v[180:183], v[4:7]
	v_mfma_f32_16x16x32_bf16 v[0:3], v[196:199], v[180:183], v[0:3]
	v_mfma_f32_16x16x32_bf16 v[52:55], v[192:195], v[160:163], v[52:55]
	v_mfma_f32_16x16x32_bf16 v[44:47], v[200:203], v[160:163], v[44:47]
	v_mfma_f32_16x16x32_bf16 v[36:39], v[192:195], v[168:171], v[36:39]
	v_mfma_f32_16x16x32_bf16 v[28:31], v[200:203], v[168:171], v[28:31]
	v_mfma_f32_16x16x32_bf16 v[20:23], v[192:195], v[176:179], v[20:23]
	v_mfma_f32_16x16x32_bf16 v[12:15], v[200:203], v[176:179], v[12:15]
	v_mfma_f32_16x16x32_bf16 v[4:7], v[192:195], v[184:187], v[4:7]
	v_mfma_f32_16x16x32_bf16 v[0:3], v[200:203], v[184:187], v[0:3]
	s_movk_i32 s46, 0x100
	s_mov_b64 s[72:73], 0
	s_mov_b64 s[70:71], -1
	s_barrier
	s_cbranch_vccz .LBB0_337
	v_mov_b32_e32 v139, v136
	s_mov_b32 s46, s29
	s_mov_b32 s47, s39
	s_lshl_b32 s45, s45, 8
	s_lshl_b32 s47, s47, 5
	s_lshl_b32 s44, s44, 8
	s_add_i32 s47, s47, s45
	v_lshrrev_b32_e32 v132, 1, v139
	v_and_or_b32 v139, v139, 15, s44
	v_and_or_b32 v132, v132, 24, s47
	v_lshl_add_u32 v140, s46, 6, v139
	v_ashrrev_i32_e32 v133, 31, v132
	v_ashrrev_i32_e32 v141, 31, v140
	v_lshl_add_u64 v[142:143], v[132:133], 1, s[34:35]
	v_lshlrev_b64 v[132:133], 12, v[140:141]
	v_lshl_add_u64 v[132:133], v[142:143], 0, v[132:133]
	v_pk_add_f32 v[126:127], v[126:127], 0 op_sel_hi:[1,0]
	v_pk_add_f32 v[124:125], v[124:125], 0 op_sel_hi:[1,0]
	v_pk_add_f32 v[144:145], v[122:123], 0 op_sel_hi:[1,0]
	v_pk_add_f32 v[122:123], v[120:121], 0 op_sel_hi:[1,0]
	v_cvt_pk_bf16_f32 v120, v124, v125
	v_cvt_pk_bf16_f32 v121, v126, v127
	v_pk_add_f32 v[116:117], v[116:117], 0 op_sel_hi:[1,0]
	v_cvt_pk_bf16_f32 v122, v122, v123
	v_cvt_pk_bf16_f32 v123, v144, v145
	global_store_dwordx4 v[132:133], v[120:123], off
	v_pk_add_f32 v[118:119], v[118:119], 0 op_sel_hi:[1,0]
	v_pk_add_f32 v[112:113], v[112:113], 0 op_sel_hi:[1,0]
	v_pk_add_f32 v[120:121], v[110:111], 0 op_sel_hi:[1,0]
	v_pk_add_f32 v[110:111], v[108:109], 0 op_sel_hi:[1,0]
	v_cvt_pk_bf16_f32 v108, v116, v117
	v_cvt_pk_bf16_f32 v109, v118, v119
	v_pk_add_f32 v[100:101], v[100:101], 0 op_sel_hi:[1,0]
	v_cvt_pk_bf16_f32 v110, v110, v111
	v_cvt_pk_bf16_f32 v111, v120, v121
	global_store_dwordx4 v[132:133], v[108:111], off offset:256
	v_pk_add_f32 v[102:103], v[102:103], 0 op_sel_hi:[1,0]
	v_pk_add_f32 v[96:97], v[96:97], 0 op_sel_hi:[1,0]
	v_or_b32_e32 v108, 16, v140
	v_ashrrev_i32_e32 v109, 31, v108
	v_lshlrev_b64 v[108:109], 12, v[108:109]
	v_lshl_add_u64 v[108:109], v[142:143], 0, v[108:109]
	v_pk_add_f32 v[110:111], v[114:115], 0 op_sel_hi:[1,0]
	v_pk_add_f32 v[114:115], v[106:107], 0 op_sel_hi:[1,0]
	v_pk_add_f32 v[106:107], v[104:105], 0 op_sel_hi:[1,0]
	v_cvt_pk_bf16_f32 v104, v112, v113
	v_cvt_pk_bf16_f32 v105, v110, v111
	v_pk_add_f32 v[84:85], v[84:85], 0 op_sel_hi:[1,0]
	v_cvt_pk_bf16_f32 v106, v106, v107
	v_cvt_pk_bf16_f32 v107, v114, v115
	global_store_dwordx4 v[108:109], v[104:107], off
	v_pk_add_f32 v[86:87], v[86:87], 0 op_sel_hi:[1,0]
	v_pk_add_f32 v[80:81], v[80:81], 0 op_sel_hi:[1,0]
	v_pk_add_f32 v[104:105], v[94:95], 0 op_sel_hi:[1,0]
	v_pk_add_f32 v[94:95], v[92:93], 0 op_sel_hi:[1,0]
	v_cvt_pk_bf16_f32 v92, v100, v101
	v_cvt_pk_bf16_f32 v93, v102, v103
	v_pk_add_f32 v[70:71], v[70:71], 0 op_sel_hi:[1,0]
	v_cvt_pk_bf16_f32 v94, v94, v95
	v_cvt_pk_bf16_f32 v95, v104, v105
	global_store_dwordx4 v[108:109], v[92:95], off offset:256
	v_pk_add_f32 v[68:69], v[68:69], 0 op_sel_hi:[1,0]
	s_mov_b64 s[44:45], 0x80000
	v_or_b32_e32 v92, 32, v140
	v_ashrrev_i32_e32 v93, 31, v92
	v_lshlrev_b64 v[92:93], 12, v[92:93]
	v_lshl_add_u64 v[92:93], v[142:143], 0, v[92:93]
	v_pk_add_f32 v[94:95], v[98:99], 0 op_sel_hi:[1,0]
	v_pk_add_f32 v[98:99], v[90:91], 0 op_sel_hi:[1,0]
	v_pk_add_f32 v[90:91], v[88:89], 0 op_sel_hi:[1,0]
	v_cvt_pk_bf16_f32 v88, v96, v97
	v_cvt_pk_bf16_f32 v89, v94, v95
	v_pk_add_f32 v[60:61], v[60:61], 0 op_sel_hi:[1,0]
	v_cvt_pk_bf16_f32 v90, v90, v91
	v_cvt_pk_bf16_f32 v91, v98, v99
	global_store_dwordx4 v[92:93], v[88:91], off
	v_pk_add_f32 v[62:63], v[62:63], 0 op_sel_hi:[1,0]
	v_pk_add_f32 v[54:55], v[54:55], 0 op_sel_hi:[1,0]
	v_pk_add_f32 v[88:89], v[78:79], 0 op_sel_hi:[1,0]
	v_pk_add_f32 v[78:79], v[76:77], 0 op_sel_hi:[1,0]
	v_cvt_pk_bf16_f32 v76, v84, v85
	v_cvt_pk_bf16_f32 v77, v86, v87
	v_pk_add_f32 v[52:53], v[52:53], 0 op_sel_hi:[1,0]
	v_cvt_pk_bf16_f32 v78, v78, v79
	v_cvt_pk_bf16_f32 v79, v88, v89
	global_store_dwordx4 v[92:93], v[76:79], off offset:256
	v_pk_add_f32 v[48:49], v[48:49], 0 op_sel_hi:[1,0]
	v_pk_add_f32 v[38:39], v[38:39], 0 op_sel_hi:[1,0]
	v_or_b32_e32 v76, 48, v140
	v_ashrrev_i32_e32 v77, 31, v76
	v_lshlrev_b64 v[76:77], 12, v[76:77]
	v_lshl_add_u64 v[76:77], v[142:143], 0, v[76:77]
	v_pk_add_f32 v[78:79], v[82:83], 0 op_sel_hi:[1,0]
	v_pk_add_f32 v[82:83], v[74:75], 0 op_sel_hi:[1,0]
	v_pk_add_f32 v[74:75], v[72:73], 0 op_sel_hi:[1,0]
	v_cvt_pk_bf16_f32 v72, v80, v81
	v_cvt_pk_bf16_f32 v73, v78, v79
	v_pk_add_f32 v[36:37], v[36:37], 0 op_sel_hi:[1,0]
	v_cvt_pk_bf16_f32 v74, v74, v75
	v_cvt_pk_bf16_f32 v75, v82, v83
	global_store_dwordx4 v[76:77], v[72:75], off
	v_pk_add_f32 v[32:33], v[32:33], 0 op_sel_hi:[1,0]
	v_pk_add_f32 v[22:23], v[22:23], 0 op_sel_hi:[1,0]
	v_pk_add_f32 v[72:73], v[66:67], 0 op_sel_hi:[1,0]
	v_pk_add_f32 v[66:67], v[64:65], 0 op_sel_hi:[1,0]
	v_cvt_pk_bf16_f32 v64, v68, v69
	v_cvt_pk_bf16_f32 v65, v70, v71
	v_pk_add_f32 v[20:21], v[20:21], 0 op_sel_hi:[1,0]
	v_cvt_pk_bf16_f32 v66, v66, v67
	v_cvt_pk_bf16_f32 v67, v72, v73
	global_store_dwordx4 v[76:77], v[64:67], off offset:256
	v_pk_add_f32 v[16:17], v[16:17], 0 op_sel_hi:[1,0]
	v_pk_add_f32 v[6:7], v[6:7], 0 op_sel_hi:[1,0]
	v_lshl_add_u64 v[64:65], v[132:133], 0, s[44:45]
	s_mov_b32 s44, 0x80000
	v_pk_add_f32 v[66:67], v[58:59], 0 op_sel_hi:[1,0]
	v_pk_add_f32 v[58:59], v[56:57], 0 op_sel_hi:[1,0]
	v_cvt_pk_bf16_f32 v56, v60, v61
	v_add_co_u32_e32 v60, vcc, s44, v132
	v_cvt_pk_bf16_f32 v57, v62, v63
	v_cvt_pk_bf16_f32 v58, v58, v59
	v_cvt_pk_bf16_f32 v59, v66, v67
	s_mov_b64 s[44:45], 0x90000
	s_nop 0
	v_addc_co_u32_e32 v61, vcc, 0, v133, vcc
	global_store_dwordx4 v[60:61], v[56:59], off
	v_pk_add_f32 v[4:5], v[4:5], 0 op_sel_hi:[1,0]
	s_mov_b64 s[66:67], -1
	v_pk_add_f32 v[56:57], v[46:47], 0 op_sel_hi:[1,0]
	v_pk_add_f32 v[46:47], v[44:45], 0 op_sel_hi:[1,0]
	v_cvt_pk_bf16_f32 v44, v52, v53
	v_cvt_pk_bf16_f32 v45, v54, v55
	s_nop 0
	v_cvt_pk_bf16_f32 v46, v46, v47
	v_cvt_pk_bf16_f32 v47, v56, v57
	global_store_dwordx4 v[64:65], v[44:47], off offset:256
	s_nop 1
	v_lshl_add_u64 v[44:45], v[132:133], 0, s[44:45]
	v_pk_add_f32 v[46:47], v[50:51], 0 op_sel_hi:[1,0]
	s_mov_b32 s44, 0x90000
	v_pk_add_f32 v[50:51], v[42:43], 0 op_sel_hi:[1,0]
	v_pk_add_f32 v[42:43], v[40:41], 0 op_sel_hi:[1,0]
	v_cvt_pk_bf16_f32 v40, v48, v49
	v_cvt_pk_bf16_f32 v41, v46, v47
	v_add_co_u32_e32 v46, vcc, s44, v132
	v_cvt_pk_bf16_f32 v42, v42, v43
	v_cvt_pk_bf16_f32 v43, v50, v51
	s_mov_b64 s[44:45], 0xa0000
	s_nop 0
	v_addc_co_u32_e32 v47, vcc, 0, v133, vcc
	global_store_dwordx4 v[46:47], v[40:43], off
	s_nop 1
	v_pk_add_f32 v[40:41], v[30:31], 0 op_sel_hi:[1,0]
	v_pk_add_f32 v[30:31], v[28:29], 0 op_sel_hi:[1,0]
	v_cvt_pk_bf16_f32 v28, v36, v37
	v_cvt_pk_bf16_f32 v29, v38, v39
	s_nop 0
	v_cvt_pk_bf16_f32 v30, v30, v31
	v_cvt_pk_bf16_f32 v31, v40, v41
	global_store_dwordx4 v[44:45], v[28:31], off offset:256
	s_nop 1
	v_lshl_add_u64 v[28:29], v[132:133], 0, s[44:45]
	v_pk_add_f32 v[30:31], v[34:35], 0 op_sel_hi:[1,0]
	s_mov_b32 s44, 0xa0000
	v_pk_add_f32 v[34:35], v[26:27], 0 op_sel_hi:[1,0]
	v_pk_add_f32 v[26:27], v[24:25], 0 op_sel_hi:[1,0]
	v_cvt_pk_bf16_f32 v24, v32, v33
	v_cvt_pk_bf16_f32 v25, v30, v31
	v_add_co_u32_e32 v30, vcc, s44, v132
	v_cvt_pk_bf16_f32 v26, v26, v27
	v_cvt_pk_bf16_f32 v27, v34, v35
	s_mov_b64 s[44:45], 0xb0000
	s_nop 0
	v_addc_co_u32_e32 v31, vcc, 0, v133, vcc
	global_store_dwordx4 v[30:31], v[24:27], off
	s_nop 1
	v_pk_add_f32 v[24:25], v[14:15], 0 op_sel_hi:[1,0]
	v_pk_add_f32 v[14:15], v[12:13], 0 op_sel_hi:[1,0]
	v_cvt_pk_bf16_f32 v12, v20, v21
	v_cvt_pk_bf16_f32 v13, v22, v23
	s_nop 0
	v_cvt_pk_bf16_f32 v14, v14, v15
	v_cvt_pk_bf16_f32 v15, v24, v25
	global_store_dwordx4 v[28:29], v[12:15], off offset:256
	s_nop 1
	v_lshl_add_u64 v[12:13], v[132:133], 0, s[44:45]
	v_pk_add_f32 v[14:15], v[18:19], 0 op_sel_hi:[1,0]
	s_mov_b32 s44, 0xb0000
	v_pk_add_f32 v[18:19], v[10:11], 0 op_sel_hi:[1,0]
	v_pk_add_f32 v[10:11], v[8:9], 0 op_sel_hi:[1,0]
	v_cvt_pk_bf16_f32 v8, v16, v17
	v_cvt_pk_bf16_f32 v9, v14, v15
	v_add_co_u32_e32 v14, vcc, s44, v132
	v_cvt_pk_bf16_f32 v10, v10, v11
	v_cvt_pk_bf16_f32 v11, v18, v19
	s_mov_b32 s44, s38
	s_nop 0
	v_addc_co_u32_e32 v15, vcc, 0, v133, vcc
	global_store_dwordx4 v[14:15], v[8:11], off
	s_nop 1
	v_pk_add_f32 v[8:9], v[2:3], 0 op_sel_hi:[1,0]
	v_pk_add_f32 v[2:3], v[0:1], 0 op_sel_hi:[1,0]
	v_cvt_pk_bf16_f32 v0, v4, v5
	v_cvt_pk_bf16_f32 v1, v6, v7
	s_nop 0
	v_cvt_pk_bf16_f32 v2, v2, v3
	v_cvt_pk_bf16_f32 v3, v8, v9
	global_store_dwordx4 v[12:13], v[0:3], off offset:256
	s_mul_i32 s46, s44, s89
	s_add_i32 s46, s46, s0
	s_cmpk_gt_i32 s46, 0x10f
	s_cbranch_scc1 .LBB0_333
	s_ashr_i32 s44, s46, 31
	s_lshr_b32 s44, s44, 29
	s_add_i32 s44, s46, s44
	s_ashr_i32 s45, s44, 3
	s_and_b32 s44, s44, -8
	s_sub_i32 s44, s46, s44
	s_cmp_lt_i32 s44, 0
	s_cselect_b32 s46, 35, 34
	s_mul_i32 s44, s46, s44
	s_add_i32 s44, s44, s45
	s_ashr_i32 s45, s44, 31
	s_lshr_b32 s45, s45, 26
	s_add_i32 s45, s44, s45
	s_ashr_i32 s46, s45, 6
	s_lshl_b32 s46, s46, 3
	s_sub_i32 s47, 34, s46
	s_min_u32 s47, s47, 8
	s_andn2_b32 s45, s45, 63
	s_sub_i32 s48, s44, s45
	v_cvt_f32_ubyte0_e32 v1, s47
	v_cvt_f32_i32_e32 v0, s48
	v_rcp_iflag_f32_e32 v2, v1
	s_ashr_i32 s44, s48, 30
	s_or_b32 s49, s44, 1
	s_mov_b64 s[66:67], 0
	v_mul_f32_e32 v2, v0, v2
	v_trunc_f32_e32 v2, v2
	v_fma_f32 v0, -v2, v1, v0
	v_cvt_i32_f32_e32 v2, v2
	v_cmp_ge_f32_e64 s[44:45], |v0|, v1
	s_and_b64 s[44:45], s[44:45], exec
	s_cselect_b32 s44, s49, 0
	v_readfirstlane_b32 s45, v2
	s_add_i32 s44, s45, s44
	s_sext_i32_i8 s45, s44
	s_mul_i32 s44, s44, s47
	s_sub_i32 s44, s48, s44
	s_sext_i32_i8 s44, s44
	s_add_i32 s44, s46, s44
	s_branch .LBB0_333

.LBB0_343:
	s_add_u32 s8, s4, 0xac33600
	s_addc_u32 s9, s5, 0
	s_add_u32 s17, s4, 0x78cb600
	s_addc_u32 s20, s5, 0
	s_add_i32 s0, s14, s13
	s_add_i32 s1, s0, -16
	s_ashr_i32 s10, s1, 31
	s_abs_i32 s1, s1
	s_mul_hi_u32 s11, s1, s16
	s_mul_i32 s11, s11, s15
	s_sub_i32 s1, s1, s11
	s_sub_i32 s11, s1, s15
	s_cmp_ge_u32 s1, s15
	s_cselect_b32 s1, s11, s1
	s_sub_i32 s11, s1, s15
	s_cmp_ge_u32 s1, s15
	s_cselect_b32 s1, s11, s1
	s_xor_b32 s1, s1, s10
	s_sub_i32 s1, s1, s10
	v_mov_b32_e32 v7, v136
	s_cmp_lg_u32 s13, 0x100
	s_cbranch_scc1 .Lrb_dft_l0
	s_sub_i32 s1, s88, 120
	s_cmp_lt_u32 s88, 204
	s_cselect_b32 s1, -1, s1
	s_cmp_lt_u32 s88, 84
	s_cselect_b32 s1, s88, s1
.Lrb_dft_l0:
	s_cmpk_gt_u32 s1, 0x7f
	v_readfirstlane_b32 s14, v7
	s_cbranch_scc1 .LBB0_367
	v_bfe_i32 v1, v7, 27, 1
	v_lshlrev_b32_e32 v0, 4, v7
	v_lshrrev_b32_e32 v1, 22, v1
	v_add_u32_e32 v1, v0, v1
	v_and_b32_e32 v1, 0xfffffc00, v1
	v_sub_u32_e32 v0, v0, v1
	v_lshrrev_b32_e32 v1, 4, v0
	v_bitop3_b32 v1, v1, v0, 32 bitop3:0x6c
	v_ashrrev_i32_e32 v0, 31, v0
	v_lshrrev_b32_e32 v0, 26, v0
	v_add_u32_e32 v0, v1, v0
	v_ashrrev_i32_e32 v4, 6, v0
	v_ashrrev_i32_e32 v0, 31, v7
	v_lshrrev_b32_e32 v0, 26, v0
	v_add_u32_e32 v0, v7, v0
	v_ashrrev_i32_e32 v5, 6, v0
	v_lshlrev_b32_e32 v0, 3, v5
	v_and_b32_e32 v0, -16, v0
	v_add_u32_e32 v0, v4, v0
	v_and_b32_e32 v2, 3, v4
	v_lshrrev_b32_e32 v3, 2, v0
	v_lshlrev_b32_e32 v6, 1, v0
	v_and_or_b32 v2, v0, 32, v2
	v_and_b32_e32 v3, 4, v3
	v_and_b32_e32 v6, 24, v6
	v_or3_b32 v2, v2, v3, v6
	v_lshrrev_b32_e32 v3, 6, v0
	v_lshl_add_u32 v2, v2, 6, v3
	s_movk_i32 s10, 0x2400
	s_lshl_b32 s11, s1, 4
	s_ashr_i32 s37, s14, 6
	v_mul_lo_u32 v2, v2, s10
	s_lshr_b32 s10, s1, 3
	s_and_b32 s11, s11, 0x70
	s_bfe_u32 s44, s1, 0x20003
	s_ashr_i32 s21, s14, 8
	s_lshl_b32 s28, s37, 10
	s_or_b32 s38, s11, s10
	s_lshl_b32 s10, s44, 18
	s_add_u32 s66, s17, s10
	v_mul_i32_i24_e32 v6, 64, v4
	s_addc_u32 s67, s20, 0
	s_lshl_b32 s10, s38, 6
	v_sub_u32_e32 v1, v1, v6
	v_mov_b32_e32 v6, 1
	s_and_b32 s10, s10, 0x1000
	s_and_b32 s11, s38, 60
	v_lshlrev_b32_e32 v3, 5, v5
	v_ashrrev_i16_sdwa v1, v6, sext(v1) dst_sel:DWORD dst_unused:UNUSED_PAD src0_sel:DWORD src1_sel:BYTE_0
	s_or_b32 s10, s10, s11
	v_and_b32_e32 v3, 32, v3
	v_bfe_i32 v6, v1, 0, 16
	s_mulk_i32 s10, 0x4800
	v_add_u32_e32 v1, v3, v6
	s_add_u32 s68, s8, s10
	v_mov_b32_e32 v133, 0
	v_add_lshl_u32 v128, v2, v1, 1
	v_lshlrev_b32_e32 v0, 10, v0
	s_addc_u32 s69, s9, 0
	v_mov_b32_e32 v129, v133
	s_add_i32 s29, s28, 0
	v_lshl_add_u32 v130, v1, 1, v0
	v_lshl_add_u64 v[0:1], s[68:69], 0, v[128:129]
	s_add_i32 m0, s29, 0x10000
	s_mov_b64 s[10:11], 0x4800
	global_load_lds_dwordx4 v128, s[68:69]
	v_lshl_add_u64 v[2:3], v[0:1], 0, s[10:11]
	s_add_i32 m0, s29, 0x12000
	v_mov_b32_e32 v131, v133
	global_load_lds_dwordx4 v[2:3], off
	v_lshl_add_u64 v[2:3], s[66:67], 0, v[130:131]
	s_mov_b32 m0, s29
	s_mov_b64 s[18:19], 0x10000
	s_add_i32 s30, s29, 0x2000
	global_load_lds_dwordx4 v130, s[66:67]
	v_lshl_add_u64 v[8:9], v[2:3], 0, s[18:19]
	s_mov_b32 m0, s30
	s_mov_b64 s[22:23], 0x9000
	global_load_lds_dwordx4 v[8:9], off
	v_lshl_add_u64 v[8:9], v[0:1], 0, s[22:23]
	s_add_i32 m0, s29, 0x14000
	s_mov_b64 s[24:25], 0xd800
	global_load_lds_dwordx4 v[8:9], off
	v_lshl_add_u64 v[8:9], v[0:1], 0, s[24:25]
	s_add_i32 m0, s29, 0x16000
	s_mov_b64 s[26:27], 0x20000
	s_add_i32 s31, s29, 0x4000
	global_load_lds_dwordx4 v[8:9], off
	v_lshl_add_u64 v[8:9], v[2:3], 0, s[26:27]
	s_mov_b32 m0, s31
	s_mov_b64 s[34:35], 0x30000
	s_add_i32 s33, s29, 0x6000
	global_load_lds_dwordx4 v[8:9], off
	v_lshl_add_u64 v[8:9], v[2:3], 0, s[34:35]
	s_mov_b32 m0, s33
	s_cmp_lg_u32 s21, 1
	global_load_lds_dwordx4 v[8:9], off
	s_mov_b32 s36, 0
	s_cbranch_scc1 .LBB0_346
	s_barrier

.LBB0_367:
	s_addk_i32 s0, 0xff70
	s_ashr_i32 s1, s0, 31
	s_abs_i32 s0, s0
	s_mul_hi_u32 s10, s0, s16
	s_mul_i32 s10, s10, s15
	s_sub_i32 s0, s0, s10
	s_sub_i32 s10, s0, s15
	s_cmp_ge_u32 s0, s15
	s_cselect_b32 s0, s10, s0
	s_sub_i32 s10, s0, s15
	s_cmp_ge_u32 s0, s15
	s_cselect_b32 s0, s10, s0
	s_xor_b32 s0, s0, s1
	s_sub_i32 s0, s0, s1
	v_mov_b32_e32 v7, v136
	s_cmp_lg_u32 s13, 0x100
	s_cbranch_scc1 .Lrb_ctx_l0
	s_sub_i32 s0, s88, 248
.Lrb_ctx_l0:
	s_cmp_gt_u32 s0, 7
	v_readfirstlane_b32 s1, v7
	s_cbranch_scc1 .LBB0_381
	v_bfe_i32 v1, v7, 27, 1
	v_lshlrev_b32_e32 v0, 4, v7
	v_lshrrev_b32_e32 v1, 22, v1
	v_add_u32_e32 v1, v0, v1
	v_and_b32_e32 v1, 0xfffffc00, v1
	v_sub_u32_e32 v0, v0, v1
	v_lshrrev_b32_e32 v1, 4, v0
	v_bitop3_b32 v1, v1, v0, 32 bitop3:0x6c
	v_ashrrev_i32_e32 v0, 31, v0
	v_lshrrev_b32_e32 v0, 26, v0
	v_add_u32_e32 v0, v1, v0
	v_ashrrev_i32_e32 v4, 6, v0
	v_ashrrev_i32_e32 v0, 31, v7
	v_lshrrev_b32_e32 v0, 26, v0
	v_add_u32_e32 v0, v7, v0
	v_ashrrev_i32_e32 v5, 6, v0
	v_lshlrev_b32_e32 v0, 3, v5
	v_and_b32_e32 v0, -16, v0
	v_add_u32_e32 v0, v4, v0
	v_and_b32_e32 v2, 3, v4
	s_mov_b32 s10, 0x3fffe0
	v_lshrrev_b32_e32 v3, 2, v0
	v_lshlrev_b32_e32 v6, 1, v0
	s_add_u32 s14, s4, 0x13c33600
	v_and_or_b32 v2, v0, s10, v2
	v_and_b32_e32 v3, 4, v3
	v_and_b32_e32 v6, 24, v6
	s_addc_u32 s15, s5, 0
	s_ashr_i32 s33, s1, 6
	v_or3_b32 v2, v2, v3, v6
	v_mul_i32_i24_e32 v6, 64, v4
	s_and_b32 s43, s0, 3
	s_ashr_i32 s16, s1, 8
	s_lshl_b32 s21, s33, 10
	v_sub_u32_e32 v1, v1, v6
	v_mov_b32_e32 v6, 1
	s_lshr_b32 s44, s0, 2
	s_lshl_b32 s10, s43, 18
	v_lshlrev_b32_e32 v3, 5, v5
	v_ashrrev_i16_sdwa v1, v6, sext(v1) dst_sel:DWORD dst_unused:UNUSED_PAD src0_sel:DWORD src1_sel:BYTE_0
	s_add_u32 s68, s17, s10
	v_and_b32_e32 v3, 32, v3
	v_bfe_i32 v6, v1, 0, 16
	s_addc_u32 s69, s20, 0
	s_mul_i32 s10, s44, 0x480000
	v_mul_u32_u24_e32 v2, 0x2400, v2
	v_add_u32_e32 v1, v3, v6
	s_add_u32 s70, s14, s10
	v_mov_b32_e32 v133, 0
	v_add_lshl_u32 v128, v2, v1, 1
	v_lshlrev_b32_e32 v0, 10, v0
	s_addc_u32 s71, s15, 0
	v_mov_b32_e32 v129, v133
	s_add_i32 s28, s21, 0
	v_lshl_add_u32 v130, v1, 1, v0
	v_lshl_add_u64 v[0:1], s[70:71], 0, v[128:129]
	s_add_i32 m0, s28, 0x10000
	s_mov_b64 s[10:11], 0x120000
	global_load_lds_dwordx4 v128, s[70:71]
	v_lshl_add_u64 v[2:3], v[0:1], 0, s[10:11]
	s_add_i32 m0, s28, 0x12000
	v_mov_b32_e32 v131, v133
	global_load_lds_dwordx4 v[2:3], off
	v_lshl_add_u64 v[2:3], s[68:69], 0, v[130:131]
	s_mov_b32 m0, s28
	s_mov_b64 s[18:19], 0x10000
	s_add_i32 s29, s28, 0x2000
	global_load_lds_dwordx4 v130, s[68:69]
	v_lshl_add_u64 v[8:9], v[2:3], 0, s[18:19]
	s_mov_b32 m0, s29
	s_mov_b64 s[22:23], 0x240000
	global_load_lds_dwordx4 v[8:9], off
	v_lshl_add_u64 v[8:9], v[0:1], 0, s[22:23]
	s_add_i32 m0, s28, 0x14000
	s_mov_b64 s[24:25], 0x360000
	global_load_lds_dwordx4 v[8:9], off
	v_lshl_add_u64 v[8:9], v[0:1], 0, s[24:25]
	s_add_i32 m0, s28, 0x16000
	s_mov_b64 s[26:27], 0x20000
	s_add_i32 s30, s28, 0x4000
	global_load_lds_dwordx4 v[8:9], off
	v_lshl_add_u64 v[8:9], v[2:3], 0, s[26:27]
	s_mov_b32 m0, s30
	s_mov_b64 s[34:35], 0x30000
	s_add_i32 s31, s28, 0x6000
	global_load_lds_dwordx4 v[8:9], off
	v_lshl_add_u64 v[8:9], v[2:3], 0, s[34:35]
	s_mov_b32 m0, s31
	s_cmp_lg_u32 s16, 1
	global_load_lds_dwordx4 v[8:9], off
	s_mov_b32 s53, 0
	s_cbranch_scc1 .LBB0_370
	s_barrier

.LBB0_993:
	s_abs_i32 s0, s13
	v_cvt_f32_u32_e32 v0, s0
	s_add_i32 s1, s14, 64
	s_ashr_i32 s8, s1, 31
	s_abs_i32 s9, s1
	v_rcp_iflag_f32_e32 v0, v0
	s_sub_i32 s1, 0, s0
	v_mov_b32_e32 v4, v136
	v_mul_f32_e32 v0, 0x4f7ffffe, v0
	v_cvt_u32_f32_e32 v0, v0
	v_readfirstlane_b32 s30, v4
	v_readfirstlane_b32 s10, v0
	s_mul_i32 s1, s1, s10
	s_mul_hi_u32 s1, s10, s1
	s_add_i32 s1, s10, s1
	s_mul_hi_u32 s10, s9, s1
	s_mul_i32 s10, s10, s0
	s_sub_i32 s9, s9, s10
	s_sub_i32 s10, s9, s0
	s_cmp_ge_u32 s9, s0
	s_cselect_b32 s9, s10, s9
	s_sub_i32 s10, s9, s0
	s_cmp_ge_u32 s9, s0
	s_cselect_b32 s9, s10, s9
	s_xor_b32 s9, s9, s8
	s_sub_i32 s15, s9, s8
	s_mov_b32 s89, s13
	s_cmp_lg_u32 s13, 0x100
	s_cbranch_scc1 .Lrb_zkv_l1
	s_sub_i32 s15, s88, 64
	s_movk_i32 s89, 192
.Lrb_zkv_l1:
	s_cmpk_gt_u32 s15, 0x10f
	s_cbranch_scc1 .LBB0_1007
	v_bfe_i32 v1, v4, 27, 1
	v_lshlrev_b32_e32 v0, 4, v4
	v_lshrrev_b32_e32 v1, 22, v1
	v_add_u32_e32 v1, v0, v1
	v_and_b32_e32 v1, 0xfffffc00, v1
	v_sub_u32_e32 v0, v0, v1
	v_ashrrev_i32_e32 v2, 31, v4
	s_add_u32 s31, s4, 0xac33e00
	v_lshrrev_b32_e32 v1, 4, v0
	v_lshrrev_b32_e32 v2, 26, v2
	s_addc_u32 s33, s5, 0
	v_bitop3_b32 v1, v1, v0, 32 bitop3:0x6c
	v_ashrrev_i32_e32 v0, 31, v0
	v_add_u32_e32 v2, v4, v2
	s_add_u32 s48, s4, 0x25cb600
	v_lshrrev_b32_e32 v0, 26, v0
	v_ashrrev_i32_e32 v2, 6, v2
	s_addc_u32 s49, s5, 0
	v_add_u32_e32 v0, v1, v0
	v_lshlrev_b32_e32 v3, 3, v2
	s_and_b32 s9, s15, 7
	v_ashrrev_i32_e32 v0, 6, v0
	v_and_b32_e32 v3, -16, v3
	s_lshr_b32 s10, s15, 3
	s_mul_i32 s9, s9, 34
	v_add_u32_e32 v3, v0, v3
	v_and_b32_e32 v5, 3, v0
	v_mul_i32_i24_e32 v0, 64, v0
	s_add_i32 s9, s9, s10
	v_lshlrev_b32_e32 v2, 5, v2
	v_sub_u32_e32 v0, v1, v0
	v_mov_b32_e32 v1, 1
	s_lshr_b32 s10, s9, 3
	s_mov_b32 s8, 0x7fffe0
	v_lshrrev_b32_e32 v6, 2, v3
	v_lshlrev_b32_e32 v7, 1, v3
	v_and_b32_e32 v2, 32, v2
	v_ashrrev_i16_sdwa v0, v1, sext(v0) dst_sel:DWORD dst_unused:UNUSED_PAD src0_sel:DWORD src1_sel:BYTE_0
	s_and_b32 s10, s10, 56
	v_and_or_b32 v5, v3, s8, v5
	v_and_b32_e32 v6, 4, v6
	v_and_b32_e32 v7, 24, v7
	v_add_u32_sdwa v0, v2, sext(v0) dst_sel:DWORD dst_unused:UNUSED_PAD src0_sel:DWORD src1_sel:WORD_0
	s_sub_i32 s11, 34, s10
	v_or3_b32 v5, v5, v6, v7
	v_lshlrev_b32_e32 v1, 1, v0
	s_min_u32 s11, s11, 8
	v_lshl_add_u32 v128, v5, 9, v1
	v_cvt_f32_ubyte0_e32 v1, s11
	v_rcp_iflag_f32_e32 v2, v1
	s_and_b32 s16, s9, 63
	v_cvt_f32_ubyte0_e32 v5, s16
	s_movk_i32 s8, 0x2400
	v_mul_f32_e32 v2, v5, v2
	v_trunc_f32_e32 v2, v2
	v_cvt_u32_f32_e32 v6, v2
	v_mul_lo_u32 v3, v3, s8
	s_ashr_i32 s24, s30, 6
	v_add_lshl_u32 v130, v0, v3, 1
	v_fma_f32 v0, -v2, v1, v5
	s_ashr_i32 s50, s30, 8
	s_lshl_b32 s51, s24, 10
	v_cmp_ge_f32_e64 s[8:9], |v0|, v1
	v_readfirstlane_b32 s17, v6
	s_cmp_lg_u64 s[8:9], 0
	s_addc_u32 s8, s17, 0
	s_mul_i32 s9, s8, s11
	s_sub_i32 s9, s16, s9
	s_and_b32 s9, s9, 0xff
	s_add_i32 s68, s10, s9
	s_mul_i32 s9, s68, 0x480000
	s_add_u32 s44, s31, s9
	s_addc_u32 s45, s33, 0
	s_and_b32 s69, s8, 0xff
	s_lshl_b32 s8, s69, 17
	s_add_u32 s46, s48, s8
	s_addc_u32 s47, s49, 0
	v_mov_b32_e32 v129, 0
	s_add_i32 s58, s51, 0
	v_lshl_add_u64 v[0:1], s[46:47], 0, v[128:129]
	s_add_i32 m0, s58, 0x10000
	s_mov_b64 s[8:9], 0x8000
	global_load_lds_dwordx4 v128, s[46:47]
	v_lshl_add_u64 v[2:3], v[0:1], 0, s[8:9]
	s_add_i32 m0, s58, 0x12000
	v_mov_b32_e32 v131, v129
	global_load_lds_dwordx4 v[2:3], off
	v_lshl_add_u64 v[2:3], s[44:45], 0, v[130:131]
	s_mov_b32 m0, s58
	s_mov_b64 s[10:11], 0x120000
	s_add_i32 s59, s58, 0x2000
	global_load_lds_dwordx4 v130, s[44:45]
	v_lshl_add_u64 v[6:7], v[2:3], 0, s[10:11]
	s_mov_b32 m0, s59
	s_mov_b64 s[16:17], 0x10000
	global_load_lds_dwordx4 v[6:7], off
	v_lshl_add_u64 v[6:7], v[0:1], 0, s[16:17]
	s_add_i32 m0, s58, 0x14000
	s_mov_b64 s[18:19], 0x18000
	global_load_lds_dwordx4 v[6:7], off
	v_lshl_add_u64 v[6:7], v[0:1], 0, s[18:19]
	s_add_i32 m0, s58, 0x16000
	s_mov_b64 s[20:21], 0x240000
	s_add_i32 s60, s58, 0x4000
	global_load_lds_dwordx4 v[6:7], off
	v_lshl_add_u64 v[6:7], v[2:3], 0, s[20:21]
	s_mov_b32 m0, s60
	s_mov_b64 s[22:23], 0x360000
	s_add_i32 s61, s58, 0x6000
	global_load_lds_dwordx4 v[6:7], off
	v_lshl_add_u64 v[6:7], v[2:3], 0, s[22:23]
	s_mov_b32 m0, s61
	s_cmp_lg_u32 s50, 1
	global_load_lds_dwordx4 v[6:7], off
	s_mov_b32 s62, 0
	s_cbranch_scc1 .LBB0_996
	s_barrier

.LBB0_998:
	s_add_i32 s62, s62, 1
	s_mul_i32 s56, s62, s89
	s_add_i32 s56, s56, s15
	s_cmpk_lt_i32 s56, 0x110
	s_mov_b64 s[52:53], 0
	s_cselect_b64 s[42:43], -1, 0
	s_cmpk_gt_i32 s56, 0x10f
	s_mov_b64 s[54:55], 0
	s_mov_b64 s[40:41], 0
	s_cbranch_scc1 .LBB0_1000
	s_ashr_i32 s40, s56, 31
	s_lshr_b32 s40, s40, 29
	s_add_i32 s40, s56, s40
	s_ashr_i32 s41, s40, 3
	s_and_b32 s40, s40, -8
	s_sub_i32 s40, s56, s40
	s_cmp_lt_i32 s40, 0
	s_cselect_b32 s54, 35, 34
	s_mul_i32 s40, s54, s40
	s_add_i32 s40, s40, s41
	s_ashr_i32 s41, s40, 31
	s_lshr_b32 s41, s41, 26
	s_add_i32 s41, s40, s41
	s_ashr_i32 s54, s41, 6
	s_lshl_b32 s55, s54, 3
	s_sub_i32 s54, 34, s55
	s_min_u32 s56, s54, 8
	s_andn2_b32 s41, s41, 63
	s_sub_i32 s57, s40, s41
	v_cvt_f32_ubyte0_e32 v1, s56
	v_cvt_f32_i32_e32 v0, s57
	v_rcp_iflag_f32_e32 v2, v1
	s_ashr_i32 s40, s57, 30
	s_or_b32 s54, s40, 1
	v_mul_f32_e32 v2, v0, v2
	v_trunc_f32_e32 v2, v2
	v_fma_f32 v0, -v2, v1, v0
	v_cvt_i32_f32_e32 v2, v2
	v_cmp_ge_f32_e64 s[40:41], |v0|, v1
	s_and_b64 s[40:41], s[40:41], exec
	s_cselect_b32 s40, s54, 0
	v_readfirstlane_b32 s41, v2
	s_add_i32 s54, s41, s40
	s_mul_i32 s40, s54, s56
	s_sub_i32 s40, s57, s40
	s_sext_i32_i8 s40, s40
	s_add_i32 s40, s55, s40
	s_bfe_i64 s[54:55], s[54:55], 0x80000
	s_mul_hi_i32 s41, s40, 0x480000
	s_mul_i32 s40, s40, 0x480000
	s_lshl_b64 s[54:55], s[54:55], 17

.LBB0_1001:
	s_add_u32 s56, s44, s70
	s_addc_u32 s57, s45, 0
	s_add_u32 s71, s56, 0x100
	s_addc_u32 s72, s57, 0
	v_cndmask_b32_e64 v132, 0, 1, s[54:55]
	s_and_b64 s[54:55], s[52:53], exec
	s_cselect_b32 s54, s40, s71
	s_cselect_b32 s55, s41, s72
	s_add_u32 s70, s46, s70
	s_addc_u32 s71, s47, 0
	ds_read_b128 v[140:143], v135
	ds_read_b128 v[144:147], v135 offset:1024
	ds_read_b128 v[148:151], v135 offset:2048
	ds_read_b128 v[152:155], v135 offset:3072
	s_add_u32 s70, s70, 0x100
	s_addc_u32 s71, s71, 0
	s_and_b64 s[52:53], s[52:53], exec
	s_cselect_b32 s52, s42, s70
	s_cselect_b32 s53, s43, s71
	s_add_i32 s73, 0, 0x1c000
	s_add_i32 s75, 0, 0x18000
	s_add_i32 s71, s73, s51
	s_add_i32 s79, s66, s51
	s_add_i32 s77, s67, s51
	s_add_i32 s74, s75, s51
	s_add_i32 s70, s71, 0x2000
	s_add_i32 m0, s58, 0xc000
	s_add_i32 s80, s58, 0xe000
	s_add_i32 s78, s79, 0x2000
	s_add_i32 s76, s77, 0x2000
	s_add_i32 s72, s74, 0x2000
	v_cmp_ne_u32_e32 vcc, 1, v132
	v_lshl_add_u64 v[132:133], s[56:57], 0, v[130:131]
	s_mov_b64 s[56:57], 0x240080
	v_lshl_add_u64 v[188:189], v[132:133], 0, s[56:57]
	s_mov_b64 s[56:57], 0x360080
	ds_read_b128 v[156:159], v137
	ds_read_b128 v[160:163], v137 offset:1024
	ds_read_b128 v[164:167], v137 offset:2048
	ds_read_b128 v[168:171], v137 offset:3072
	ds_read_b128 v[172:175], v137 offset:4096
	ds_read_b128 v[176:179], v137 offset:5120
	ds_read_b128 v[180:183], v137 offset:6144
	ds_read_b128 v[184:187], v137 offset:7168
	global_load_lds_dwordx4 v[188:189], off
	v_lshl_add_u64 v[132:133], v[132:133], 0, s[56:57]
	s_mov_b32 m0, s80
	s_nop 0
	global_load_lds_dwordx4 v[132:133], off
	s_waitcnt lgkmcnt(8)
	s_barrier
	s_waitcnt lgkmcnt(0)
	s_waitcnt lgkmcnt(0)
	v_mfma_f32_16x16x32_bf16 v[124:127], v[140:143], v[156:159], v[124:127]
	v_mfma_f32_16x16x32_bf16 v[120:123], v[148:151], v[156:159], v[120:123]
	v_mfma_f32_16x16x32_bf16 v[112:115], v[140:143], v[164:167], v[112:115]
	v_mfma_f32_16x16x32_bf16 v[104:107], v[148:151], v[164:167], v[104:107]
	v_mfma_f32_16x16x32_bf16 v[96:99], v[140:143], v[172:175], v[96:99]
	v_mfma_f32_16x16x32_bf16 v[88:91], v[148:151], v[172:175], v[88:91]
	v_mfma_f32_16x16x32_bf16 v[80:83], v[140:143], v[180:183], v[80:83]
	v_mfma_f32_16x16x32_bf16 v[72:75], v[148:151], v[180:183], v[72:75]
	v_mfma_f32_16x16x32_bf16 v[124:127], v[144:147], v[160:163], v[124:127]
	v_mfma_f32_16x16x32_bf16 v[120:123], v[152:155], v[160:163], v[120:123]
	v_mfma_f32_16x16x32_bf16 v[112:115], v[144:147], v[168:171], v[112:115]
	v_mfma_f32_16x16x32_bf16 v[104:107], v[152:155], v[168:171], v[104:107]
	v_mfma_f32_16x16x32_bf16 v[96:99], v[144:147], v[176:179], v[96:99]
	v_mfma_f32_16x16x32_bf16 v[88:91], v[152:155], v[176:179], v[88:91]
	v_mfma_f32_16x16x32_bf16 v[80:83], v[144:147], v[184:187], v[80:83]
	v_mfma_f32_16x16x32_bf16 v[72:75], v[152:155], v[184:187], v[72:75]
	s_barrier
	s_mov_b32 m0, s79
	v_lshl_add_u64 v[132:133], s[52:53], 0, v[128:129]
	ds_read_b128 v[188:191], v138
	ds_read_b128 v[192:195], v138 offset:1024
	ds_read_b128 v[196:199], v138 offset:2048
	ds_read_b128 v[200:203], v138 offset:3072
	global_load_lds_dwordx4 v[132:133], off
	v_lshl_add_u64 v[204:205], v[132:133], 0, s[8:9]
	s_mov_b32 m0, s78
	s_nop 0
	global_load_lds_dwordx4 v[204:205], off
	s_barrier
	s_waitcnt lgkmcnt(0)
	s_waitcnt lgkmcnt(0)
	v_mfma_f32_16x16x32_bf16 v[116:119], v[188:191], v[156:159], v[116:119]
	v_mfma_f32_16x16x32_bf16 v[108:111], v[196:199], v[156:159], v[108:111]
	v_mfma_f32_16x16x32_bf16 v[100:103], v[188:191], v[164:167], v[100:103]
	v_mfma_f32_16x16x32_bf16 v[92:95], v[196:199], v[164:167], v[92:95]
	v_mfma_f32_16x16x32_bf16 v[84:87], v[188:191], v[172:175], v[84:87]
	v_mfma_f32_16x16x32_bf16 v[76:79], v[196:199], v[172:175], v[76:79]
	v_mfma_f32_16x16x32_bf16 v[68:71], v[188:191], v[180:183], v[68:71]
	v_mfma_f32_16x16x32_bf16 v[64:67], v[196:199], v[180:183], v[64:67]
	v_mfma_f32_16x16x32_bf16 v[116:119], v[192:195], v[160:163], v[116:119]
	v_mfma_f32_16x16x32_bf16 v[108:111], v[200:203], v[160:163], v[108:111]
	v_mfma_f32_16x16x32_bf16 v[100:103], v[192:195], v[168:171], v[100:103]
	v_mfma_f32_16x16x32_bf16 v[92:95], v[200:203], v[168:171], v[92:95]
	v_mfma_f32_16x16x32_bf16 v[84:87], v[192:195], v[176:179], v[84:87]
	v_mfma_f32_16x16x32_bf16 v[76:79], v[200:203], v[176:179], v[76:79]
	v_mfma_f32_16x16x32_bf16 v[68:71], v[192:195], v[184:187], v[68:71]
	v_mfma_f32_16x16x32_bf16 v[64:67], v[200:203], v[184:187], v[64:67]
	s_mov_b32 m0, s58
	v_lshl_add_u64 v[204:205], s[54:55], 0, v[130:131]
	s_barrier
	ds_read_b128 v[156:159], v137 offset:16384
	ds_read_b128 v[160:163], v137 offset:17408
	ds_read_b128 v[164:167], v137 offset:18432
	ds_read_b128 v[168:171], v137 offset:19456
	ds_read_b128 v[172:175], v137 offset:20480
	ds_read_b128 v[176:179], v137 offset:21504
	ds_read_b128 v[180:183], v137 offset:22528
	ds_read_b128 v[184:187], v137 offset:23552
	global_load_lds_dwordx4 v[204:205], off
	v_lshl_add_u64 v[206:207], v[204:205], 0, s[10:11]
	s_mov_b32 m0, s59
	s_nop 0
	global_load_lds_dwordx4 v[206:207], off
	s_barrier
	s_waitcnt lgkmcnt(0)
	s_waitcnt lgkmcnt(0)
	v_mfma_f32_16x16x32_bf16 v[60:63], v[140:143], v[156:159], v[60:63]
	v_mfma_f32_16x16x32_bf16 v[56:59], v[148:151], v[156:159], v[56:59]
	v_mfma_f32_16x16x32_bf16 v[48:51], v[140:143], v[164:167], v[48:51]
	v_mfma_f32_16x16x32_bf16 v[40:43], v[148:151], v[164:167], v[40:43]
	v_mfma_f32_16x16x32_bf16 v[32:35], v[140:143], v[172:175], v[32:35]
	v_mfma_f32_16x16x32_bf16 v[24:27], v[148:151], v[172:175], v[24:27]
	v_mfma_f32_16x16x32_bf16 v[16:19], v[140:143], v[180:183], v[16:19]
	v_mfma_f32_16x16x32_bf16 v[8:11], v[148:151], v[180:183], v[8:11]
	v_mfma_f32_16x16x32_bf16 v[60:63], v[144:147], v[160:163], v[60:63]
	v_mfma_f32_16x16x32_bf16 v[56:59], v[152:155], v[160:163], v[56:59]
	v_mfma_f32_16x16x32_bf16 v[48:51], v[144:147], v[168:171], v[48:51]
	v_mfma_f32_16x16x32_bf16 v[40:43], v[152:155], v[168:171], v[40:43]
	v_mfma_f32_16x16x32_bf16 v[32:35], v[144:147], v[176:179], v[32:35]
	v_mfma_f32_16x16x32_bf16 v[24:27], v[152:155], v[176:179], v[24:27]
	v_mfma_f32_16x16x32_bf16 v[16:19], v[144:147], v[184:187], v[16:19]
	v_mfma_f32_16x16x32_bf16 v[8:11], v[152:155], v[184:187], v[8:11]
	s_barrier
	s_mov_b32 m0, s77
	v_lshl_add_u64 v[140:141], v[132:133], 0, s[16:17]
	global_load_lds_dwordx4 v[140:141], off
	v_lshl_add_u64 v[140:141], v[132:133], 0, s[18:19]
	s_mov_b32 m0, s76
	s_nop 0
	global_load_lds_dwordx4 v[140:141], off
	s_waitcnt vmcnt(6)
	s_barrier
	v_mfma_f32_16x16x32_bf16 v[52:55], v[188:191], v[156:159], v[52:55]
	v_mfma_f32_16x16x32_bf16 v[44:47], v[196:199], v[156:159], v[44:47]
	v_mfma_f32_16x16x32_bf16 v[36:39], v[188:191], v[164:167], v[36:39]
	v_mfma_f32_16x16x32_bf16 v[28:31], v[196:199], v[164:167], v[28:31]
	v_mfma_f32_16x16x32_bf16 v[20:23], v[188:191], v[172:175], v[20:23]
	v_mfma_f32_16x16x32_bf16 v[12:15], v[196:199], v[172:175], v[12:15]
	v_mfma_f32_16x16x32_bf16 v[4:7], v[188:191], v[180:183], v[4:7]
	v_mfma_f32_16x16x32_bf16 v[0:3], v[196:199], v[180:183], v[0:3]
	v_mfma_f32_16x16x32_bf16 v[52:55], v[192:195], v[160:163], v[52:55]
	v_mfma_f32_16x16x32_bf16 v[44:47], v[200:203], v[160:163], v[44:47]
	v_mfma_f32_16x16x32_bf16 v[36:39], v[192:195], v[168:171], v[36:39]
	v_mfma_f32_16x16x32_bf16 v[28:31], v[200:203], v[168:171], v[28:31]
	v_mfma_f32_16x16x32_bf16 v[20:23], v[192:195], v[176:179], v[20:23]
	v_mfma_f32_16x16x32_bf16 v[12:15], v[200:203], v[176:179], v[12:15]
	v_mfma_f32_16x16x32_bf16 v[4:7], v[192:195], v[184:187], v[4:7]
	v_mfma_f32_16x16x32_bf16 v[0:3], v[200:203], v[184:187], v[0:3]
	v_add_u32_e32 v139, s75, v134
	s_barrier
	ds_read_b128 v[140:143], v139
	ds_read_b128 v[144:147], v139 offset:1024
	ds_read_b128 v[148:151], v139 offset:2048
	ds_read_b128 v[152:155], v139 offset:3072
	s_mov_b32 m0, s60
	v_lshl_add_u64 v[188:189], v[204:205], 0, s[20:21]
	ds_read_b128 v[156:159], v137 offset:32768
	ds_read_b128 v[160:163], v137 offset:33792
	ds_read_b128 v[164:167], v137 offset:34816
	ds_read_b128 v[168:171], v137 offset:35840
	ds_read_b128 v[172:175], v137 offset:36864
	ds_read_b128 v[176:179], v137 offset:37888
	ds_read_b128 v[180:183], v137 offset:38912
	ds_read_b128 v[184:187], v137 offset:39936
	global_load_lds_dwordx4 v[188:189], off
	v_lshl_add_u64 v[188:189], v[204:205], 0, s[22:23]
	s_mov_b32 m0, s61
	s_nop 0
	global_load_lds_dwordx4 v[188:189], off
	s_waitcnt lgkmcnt(8)
	s_barrier
	s_waitcnt lgkmcnt(0)
	s_waitcnt lgkmcnt(0)
	v_mfma_f32_16x16x32_bf16 v[124:127], v[140:143], v[156:159], v[124:127]
	v_mfma_f32_16x16x32_bf16 v[120:123], v[148:151], v[156:159], v[120:123]
	v_mfma_f32_16x16x32_bf16 v[112:115], v[140:143], v[164:167], v[112:115]
	v_mfma_f32_16x16x32_bf16 v[104:107], v[148:151], v[164:167], v[104:107]
	v_mfma_f32_16x16x32_bf16 v[96:99], v[140:143], v[172:175], v[96:99]
	v_mfma_f32_16x16x32_bf16 v[88:91], v[148:151], v[172:175], v[88:91]
	v_mfma_f32_16x16x32_bf16 v[80:83], v[140:143], v[180:183], v[80:83]
	v_mfma_f32_16x16x32_bf16 v[72:75], v[148:151], v[180:183], v[72:75]
	v_mfma_f32_16x16x32_bf16 v[124:127], v[144:147], v[160:163], v[124:127]
	v_mfma_f32_16x16x32_bf16 v[120:123], v[152:155], v[160:163], v[120:123]
	v_mfma_f32_16x16x32_bf16 v[112:115], v[144:147], v[168:171], v[112:115]
	v_mfma_f32_16x16x32_bf16 v[104:107], v[152:155], v[168:171], v[104:107]
	v_mfma_f32_16x16x32_bf16 v[96:99], v[144:147], v[176:179], v[96:99]
	v_mfma_f32_16x16x32_bf16 v[88:91], v[152:155], v[176:179], v[88:91]
	v_mfma_f32_16x16x32_bf16 v[80:83], v[144:147], v[184:187], v[80:83]
	v_mfma_f32_16x16x32_bf16 v[72:75], v[152:155], v[184:187], v[72:75]
	s_barrier
	s_mov_b32 m0, s74
	v_add_u32_e32 v139, s73, v134
	v_lshl_add_u64 v[206:207], v[132:133], 0, s[26:27]
	ds_read_b128 v[188:191], v139
	ds_read_b128 v[192:195], v139 offset:1024
	ds_read_b128 v[196:199], v139 offset:2048
	ds_read_b128 v[200:203], v139 offset:3072
	global_load_lds_dwordx4 v[206:207], off
	v_lshl_add_u64 v[206:207], v[132:133], 0, s[28:29]
	s_mov_b32 m0, s72
	s_nop 0
	global_load_lds_dwordx4 v[206:207], off
	s_barrier
	s_waitcnt lgkmcnt(0)
	s_waitcnt lgkmcnt(0)
	v_mfma_f32_16x16x32_bf16 v[116:119], v[188:191], v[156:159], v[116:119]
	v_mfma_f32_16x16x32_bf16 v[108:111], v[196:199], v[156:159], v[108:111]
	v_mfma_f32_16x16x32_bf16 v[100:103], v[188:191], v[164:167], v[100:103]
	v_mfma_f32_16x16x32_bf16 v[92:95], v[196:199], v[164:167], v[92:95]
	v_mfma_f32_16x16x32_bf16 v[84:87], v[188:191], v[172:175], v[84:87]
	v_mfma_f32_16x16x32_bf16 v[76:79], v[196:199], v[172:175], v[76:79]
	v_mfma_f32_16x16x32_bf16 v[68:71], v[188:191], v[180:183], v[68:71]
	v_mfma_f32_16x16x32_bf16 v[64:67], v[196:199], v[180:183], v[64:67]
	v_mfma_f32_16x16x32_bf16 v[116:119], v[192:195], v[160:163], v[116:119]
	v_mfma_f32_16x16x32_bf16 v[108:111], v[200:203], v[160:163], v[108:111]
	v_mfma_f32_16x16x32_bf16 v[100:103], v[192:195], v[168:171], v[100:103]
	v_mfma_f32_16x16x32_bf16 v[92:95], v[200:203], v[168:171], v[92:95]
	v_mfma_f32_16x16x32_bf16 v[84:87], v[192:195], v[176:179], v[84:87]
	v_mfma_f32_16x16x32_bf16 v[76:79], v[200:203], v[176:179], v[76:79]
	v_mfma_f32_16x16x32_bf16 v[68:71], v[192:195], v[184:187], v[68:71]
	v_mfma_f32_16x16x32_bf16 v[64:67], v[200:203], v[184:187], v[64:67]
	s_mov_b32 m0, s64
	v_lshl_add_u64 v[206:207], v[204:205], 0, s[26:27]
	s_barrier
	ds_read_b128 v[156:159], v137 offset:49152
	ds_read_b128 v[160:163], v137 offset:50176
	ds_read_b128 v[164:167], v137 offset:51200
	ds_read_b128 v[168:171], v137 offset:52224
	ds_read_b128 v[172:175], v137 offset:53248
	ds_read_b128 v[176:179], v137 offset:54272
	ds_read_b128 v[180:183], v137 offset:55296
	ds_read_b128 v[184:187], v137 offset:56320
	global_load_lds_dwordx4 v[206:207], off
	v_lshl_add_u64 v[204:205], v[204:205], 0, s[34:35]
	s_mov_b32 m0, s65
	s_nop 0
	global_load_lds_dwordx4 v[204:205], off
	s_barrier
	s_waitcnt lgkmcnt(0)
	s_waitcnt lgkmcnt(0)
	v_mfma_f32_16x16x32_bf16 v[60:63], v[140:143], v[156:159], v[60:63]
	v_mfma_f32_16x16x32_bf16 v[56:59], v[148:151], v[156:159], v[56:59]
	v_mfma_f32_16x16x32_bf16 v[48:51], v[140:143], v[164:167], v[48:51]
	v_mfma_f32_16x16x32_bf16 v[40:43], v[148:151], v[164:167], v[40:43]
	v_mfma_f32_16x16x32_bf16 v[32:35], v[140:143], v[172:175], v[32:35]
	v_mfma_f32_16x16x32_bf16 v[24:27], v[148:151], v[172:175], v[24:27]
	v_mfma_f32_16x16x32_bf16 v[16:19], v[140:143], v[180:183], v[16:19]
	v_mfma_f32_16x16x32_bf16 v[8:11], v[148:151], v[180:183], v[8:11]
	v_mfma_f32_16x16x32_bf16 v[60:63], v[144:147], v[160:163], v[60:63]
	v_mfma_f32_16x16x32_bf16 v[56:59], v[152:155], v[160:163], v[56:59]
	v_mfma_f32_16x16x32_bf16 v[48:51], v[144:147], v[168:171], v[48:51]
	v_mfma_f32_16x16x32_bf16 v[40:43], v[152:155], v[168:171], v[40:43]
	v_mfma_f32_16x16x32_bf16 v[32:35], v[144:147], v[176:179], v[32:35]
	v_mfma_f32_16x16x32_bf16 v[24:27], v[152:155], v[176:179], v[24:27]
	v_mfma_f32_16x16x32_bf16 v[16:19], v[144:147], v[184:187], v[16:19]
	v_mfma_f32_16x16x32_bf16 v[8:11], v[152:155], v[184:187], v[8:11]
	s_barrier
	s_mov_b32 m0, s71
	v_lshl_add_u64 v[140:141], v[132:133], 0, s[36:37]
	global_load_lds_dwordx4 v[140:141], off
	v_lshl_add_u64 v[132:133], v[132:133], 0, s[38:39]
	s_mov_b32 m0, s70
	s_nop 0
	global_load_lds_dwordx4 v[132:133], off
	s_waitcnt vmcnt(6)
	s_barrier
	v_mfma_f32_16x16x32_bf16 v[52:55], v[188:191], v[156:159], v[52:55]
	v_mfma_f32_16x16x32_bf16 v[44:47], v[196:199], v[156:159], v[44:47]
	v_mfma_f32_16x16x32_bf16 v[36:39], v[188:191], v[164:167], v[36:39]
	v_mfma_f32_16x16x32_bf16 v[28:31], v[196:199], v[164:167], v[28:31]
	v_mfma_f32_16x16x32_bf16 v[20:23], v[188:191], v[172:175], v[20:23]
	v_mfma_f32_16x16x32_bf16 v[12:15], v[196:199], v[172:175], v[12:15]
	v_mfma_f32_16x16x32_bf16 v[4:7], v[188:191], v[180:183], v[4:7]
	v_mfma_f32_16x16x32_bf16 v[0:3], v[196:199], v[180:183], v[0:3]
	v_mfma_f32_16x16x32_bf16 v[52:55], v[192:195], v[160:163], v[52:55]
	v_mfma_f32_16x16x32_bf16 v[44:47], v[200:203], v[160:163], v[44:47]
	v_mfma_f32_16x16x32_bf16 v[36:39], v[192:195], v[168:171], v[36:39]
	v_mfma_f32_16x16x32_bf16 v[28:31], v[200:203], v[168:171], v[28:31]
	v_mfma_f32_16x16x32_bf16 v[20:23], v[192:195], v[176:179], v[20:23]
	v_mfma_f32_16x16x32_bf16 v[12:15], v[200:203], v[176:179], v[12:15]
	v_mfma_f32_16x16x32_bf16 v[4:7], v[192:195], v[184:187], v[4:7]
	v_mfma_f32_16x16x32_bf16 v[0:3], v[200:203], v[184:187], v[0:3]
	s_movk_i32 s70, 0x100
	s_mov_b64 s[54:55], 0
	s_mov_b64 s[52:53], -1
	s_barrier
	s_cbranch_vccz .LBB0_1001
	v_mov_b32_e32 v139, v136
	s_mov_b32 s44, s50
	s_mov_b32 s45, s63
	s_lshl_b32 s46, s69, 8
	s_lshl_b32 s45, s45, 5
	s_add_i32 s45, s45, s46
	v_lshrrev_b32_e32 v132, 1, v139
	v_and_or_b32 v132, v132, 24, s45
	s_lshl_b32 s45, s68, 8
	v_and_or_b32 v139, v139, 15, s45
	v_lshl_add_u32 v140, s44, 6, v139
	v_ashrrev_i32_e32 v133, 31, v132
	v_ashrrev_i32_e32 v141, 31, v140
	v_lshl_add_u64 v[142:143], v[132:133], 1, s[24:25]
	v_lshlrev_b64 v[132:133], 12, v[140:141]
	v_lshl_add_u64 v[132:133], v[142:143], 0, v[132:133]
	v_pk_add_f32 v[126:127], v[126:127], 0 op_sel_hi:[1,0]
	v_pk_add_f32 v[124:125], v[124:125], 0 op_sel_hi:[1,0]
	v_pk_add_f32 v[144:145], v[122:123], 0 op_sel_hi:[1,0]
	v_pk_add_f32 v[122:123], v[120:121], 0 op_sel_hi:[1,0]
	v_cvt_pk_bf16_f32 v120, v124, v125
	v_cvt_pk_bf16_f32 v121, v126, v127
	v_pk_add_f32 v[116:117], v[116:117], 0 op_sel_hi:[1,0]
	v_cvt_pk_bf16_f32 v122, v122, v123
	v_cvt_pk_bf16_f32 v123, v144, v145
	global_store_dwordx4 v[132:133], v[120:123], off
	v_pk_add_f32 v[118:119], v[118:119], 0 op_sel_hi:[1,0]
	v_pk_add_f32 v[112:113], v[112:113], 0 op_sel_hi:[1,0]
	v_pk_add_f32 v[120:121], v[110:111], 0 op_sel_hi:[1,0]
	v_pk_add_f32 v[110:111], v[108:109], 0 op_sel_hi:[1,0]
	v_cvt_pk_bf16_f32 v108, v116, v117
	v_cvt_pk_bf16_f32 v109, v118, v119
	v_pk_add_f32 v[100:101], v[100:101], 0 op_sel_hi:[1,0]
	v_cvt_pk_bf16_f32 v110, v110, v111
	v_cvt_pk_bf16_f32 v111, v120, v121
	global_store_dwordx4 v[132:133], v[108:111], off offset:256
	v_pk_add_f32 v[102:103], v[102:103], 0 op_sel_hi:[1,0]
	v_pk_add_f32 v[96:97], v[96:97], 0 op_sel_hi:[1,0]
	v_or_b32_e32 v108, 16, v140
	v_ashrrev_i32_e32 v109, 31, v108
	v_lshlrev_b64 v[108:109], 12, v[108:109]
	v_lshl_add_u64 v[108:109], v[142:143], 0, v[108:109]
	v_pk_add_f32 v[110:111], v[114:115], 0 op_sel_hi:[1,0]
	v_pk_add_f32 v[114:115], v[106:107], 0 op_sel_hi:[1,0]
	v_pk_add_f32 v[106:107], v[104:105], 0 op_sel_hi:[1,0]
	v_cvt_pk_bf16_f32 v104, v112, v113
	v_cvt_pk_bf16_f32 v105, v110, v111
	v_pk_add_f32 v[84:85], v[84:85], 0 op_sel_hi:[1,0]
	v_cvt_pk_bf16_f32 v106, v106, v107
	v_cvt_pk_bf16_f32 v107, v114, v115
	global_store_dwordx4 v[108:109], v[104:107], off
	v_pk_add_f32 v[86:87], v[86:87], 0 op_sel_hi:[1,0]
	v_pk_add_f32 v[80:81], v[80:81], 0 op_sel_hi:[1,0]
	v_pk_add_f32 v[104:105], v[94:95], 0 op_sel_hi:[1,0]
	v_pk_add_f32 v[94:95], v[92:93], 0 op_sel_hi:[1,0]
	v_cvt_pk_bf16_f32 v92, v100, v101
	v_cvt_pk_bf16_f32 v93, v102, v103
	v_pk_add_f32 v[70:71], v[70:71], 0 op_sel_hi:[1,0]
	v_cvt_pk_bf16_f32 v94, v94, v95
	v_cvt_pk_bf16_f32 v95, v104, v105
	global_store_dwordx4 v[108:109], v[92:95], off offset:256
	v_pk_add_f32 v[68:69], v[68:69], 0 op_sel_hi:[1,0]
	s_mov_b64 s[44:45], 0x80000
	v_or_b32_e32 v92, 32, v140
	v_ashrrev_i32_e32 v93, 31, v92
	v_lshlrev_b64 v[92:93], 12, v[92:93]
	v_lshl_add_u64 v[92:93], v[142:143], 0, v[92:93]
	v_pk_add_f32 v[94:95], v[98:99], 0 op_sel_hi:[1,0]
	v_pk_add_f32 v[98:99], v[90:91], 0 op_sel_hi:[1,0]
	v_pk_add_f32 v[90:91], v[88:89], 0 op_sel_hi:[1,0]
	v_cvt_pk_bf16_f32 v88, v96, v97
	v_cvt_pk_bf16_f32 v89, v94, v95
	v_pk_add_f32 v[60:61], v[60:61], 0 op_sel_hi:[1,0]
	v_cvt_pk_bf16_f32 v90, v90, v91
	v_cvt_pk_bf16_f32 v91, v98, v99
	global_store_dwordx4 v[92:93], v[88:91], off
	v_pk_add_f32 v[62:63], v[62:63], 0 op_sel_hi:[1,0]
	v_pk_add_f32 v[54:55], v[54:55], 0 op_sel_hi:[1,0]
	v_pk_add_f32 v[88:89], v[78:79], 0 op_sel_hi:[1,0]
	v_pk_add_f32 v[78:79], v[76:77], 0 op_sel_hi:[1,0]
	v_cvt_pk_bf16_f32 v76, v84, v85
	v_cvt_pk_bf16_f32 v77, v86, v87
	v_pk_add_f32 v[52:53], v[52:53], 0 op_sel_hi:[1,0]
	v_cvt_pk_bf16_f32 v78, v78, v79
	v_cvt_pk_bf16_f32 v79, v88, v89
	global_store_dwordx4 v[92:93], v[76:79], off offset:256
	v_pk_add_f32 v[48:49], v[48:49], 0 op_sel_hi:[1,0]
	v_pk_add_f32 v[38:39], v[38:39], 0 op_sel_hi:[1,0]
	v_or_b32_e32 v76, 48, v140
	v_ashrrev_i32_e32 v77, 31, v76
	v_lshlrev_b64 v[76:77], 12, v[76:77]
	v_lshl_add_u64 v[76:77], v[142:143], 0, v[76:77]
	v_pk_add_f32 v[78:79], v[82:83], 0 op_sel_hi:[1,0]
	v_pk_add_f32 v[82:83], v[74:75], 0 op_sel_hi:[1,0]
	v_pk_add_f32 v[74:75], v[72:73], 0 op_sel_hi:[1,0]
	v_cvt_pk_bf16_f32 v72, v80, v81
	v_cvt_pk_bf16_f32 v73, v78, v79
	v_pk_add_f32 v[36:37], v[36:37], 0 op_sel_hi:[1,0]
	v_cvt_pk_bf16_f32 v74, v74, v75
	v_cvt_pk_bf16_f32 v75, v82, v83
	global_store_dwordx4 v[76:77], v[72:75], off
	v_pk_add_f32 v[32:33], v[32:33], 0 op_sel_hi:[1,0]
	v_pk_add_f32 v[22:23], v[22:23], 0 op_sel_hi:[1,0]
	v_pk_add_f32 v[72:73], v[66:67], 0 op_sel_hi:[1,0]
	v_pk_add_f32 v[66:67], v[64:65], 0 op_sel_hi:[1,0]
	v_cvt_pk_bf16_f32 v64, v68, v69
	v_cvt_pk_bf16_f32 v65, v70, v71
	v_pk_add_f32 v[20:21], v[20:21], 0 op_sel_hi:[1,0]
	v_cvt_pk_bf16_f32 v66, v66, v67
	v_cvt_pk_bf16_f32 v67, v72, v73
	global_store_dwordx4 v[76:77], v[64:67], off offset:256
	v_pk_add_f32 v[16:17], v[16:17], 0 op_sel_hi:[1,0]
	v_pk_add_f32 v[6:7], v[6:7], 0 op_sel_hi:[1,0]
	v_lshl_add_u64 v[64:65], v[132:133], 0, s[44:45]
	s_mov_b32 s44, 0x80000
	v_pk_add_f32 v[66:67], v[58:59], 0 op_sel_hi:[1,0]
	v_pk_add_f32 v[58:59], v[56:57], 0 op_sel_hi:[1,0]
	v_cvt_pk_bf16_f32 v56, v60, v61
	v_add_co_u32_e32 v60, vcc, s44, v132
	v_cvt_pk_bf16_f32 v57, v62, v63
	v_cvt_pk_bf16_f32 v58, v58, v59
	v_cvt_pk_bf16_f32 v59, v66, v67
	s_mov_b64 s[44:45], 0x90000
	s_nop 0
	v_addc_co_u32_e32 v61, vcc, 0, v133, vcc
	global_store_dwordx4 v[60:61], v[56:59], off
	v_pk_add_f32 v[4:5], v[4:5], 0 op_sel_hi:[1,0]
	s_nop 0
	v_pk_add_f32 v[56:57], v[46:47], 0 op_sel_hi:[1,0]
	v_pk_add_f32 v[46:47], v[44:45], 0 op_sel_hi:[1,0]
	v_cvt_pk_bf16_f32 v44, v52, v53
	v_cvt_pk_bf16_f32 v45, v54, v55
	s_nop 0
	v_cvt_pk_bf16_f32 v46, v46, v47
	v_cvt_pk_bf16_f32 v47, v56, v57
	global_store_dwordx4 v[64:65], v[44:47], off offset:256
	s_nop 1
	v_lshl_add_u64 v[44:45], v[132:133], 0, s[44:45]
	v_pk_add_f32 v[46:47], v[50:51], 0 op_sel_hi:[1,0]
	s_mov_b32 s44, 0x90000
	v_pk_add_f32 v[50:51], v[42:43], 0 op_sel_hi:[1,0]
	v_pk_add_f32 v[42:43], v[40:41], 0 op_sel_hi:[1,0]
	v_cvt_pk_bf16_f32 v40, v48, v49
	v_cvt_pk_bf16_f32 v41, v46, v47
	v_add_co_u32_e32 v46, vcc, s44, v132
	v_cvt_pk_bf16_f32 v42, v42, v43
	v_cvt_pk_bf16_f32 v43, v50, v51
	s_mov_b64 s[44:45], 0xa0000
	s_nop 0
	v_addc_co_u32_e32 v47, vcc, 0, v133, vcc
	global_store_dwordx4 v[46:47], v[40:43], off
	s_nop 1
	v_pk_add_f32 v[40:41], v[30:31], 0 op_sel_hi:[1,0]
	v_pk_add_f32 v[30:31], v[28:29], 0 op_sel_hi:[1,0]
	v_cvt_pk_bf16_f32 v28, v36, v37
	v_cvt_pk_bf16_f32 v29, v38, v39
	s_nop 0
	v_cvt_pk_bf16_f32 v30, v30, v31
	v_cvt_pk_bf16_f32 v31, v40, v41
	global_store_dwordx4 v[44:45], v[28:31], off offset:256
	s_nop 1
	v_lshl_add_u64 v[28:29], v[132:133], 0, s[44:45]
	v_pk_add_f32 v[30:31], v[34:35], 0 op_sel_hi:[1,0]
	s_mov_b32 s44, 0xa0000
	v_pk_add_f32 v[34:35], v[26:27], 0 op_sel_hi:[1,0]
	v_pk_add_f32 v[26:27], v[24:25], 0 op_sel_hi:[1,0]
	v_cvt_pk_bf16_f32 v24, v32, v33
	v_cvt_pk_bf16_f32 v25, v30, v31
	v_add_co_u32_e32 v30, vcc, s44, v132
	v_cvt_pk_bf16_f32 v26, v26, v27
	v_cvt_pk_bf16_f32 v27, v34, v35
	s_mov_b64 s[44:45], 0xb0000
	s_nop 0
	v_addc_co_u32_e32 v31, vcc, 0, v133, vcc
	global_store_dwordx4 v[30:31], v[24:27], off
	s_nop 1
	v_pk_add_f32 v[24:25], v[14:15], 0 op_sel_hi:[1,0]
	v_pk_add_f32 v[14:15], v[12:13], 0 op_sel_hi:[1,0]
	v_cvt_pk_bf16_f32 v12, v20, v21
	v_cvt_pk_bf16_f32 v13, v22, v23
	s_nop 0
	v_cvt_pk_bf16_f32 v14, v14, v15
	v_cvt_pk_bf16_f32 v15, v24, v25
	global_store_dwordx4 v[28:29], v[12:15], off offset:256
	s_nop 1
	v_lshl_add_u64 v[12:13], v[132:133], 0, s[44:45]
	v_pk_add_f32 v[14:15], v[18:19], 0 op_sel_hi:[1,0]
	s_mov_b32 s44, 0xb0000
	v_pk_add_f32 v[18:19], v[10:11], 0 op_sel_hi:[1,0]
	v_pk_add_f32 v[10:11], v[8:9], 0 op_sel_hi:[1,0]
	v_cvt_pk_bf16_f32 v8, v16, v17
	v_cvt_pk_bf16_f32 v9, v14, v15
	v_add_co_u32_e32 v14, vcc, s44, v132
	v_cvt_pk_bf16_f32 v10, v10, v11
	v_cvt_pk_bf16_f32 v11, v18, v19
	s_mov_b32 s44, s62
	s_nop 0
	v_addc_co_u32_e32 v15, vcc, 0, v133, vcc
	global_store_dwordx4 v[14:15], v[8:11], off
	s_nop 1
	v_pk_add_f32 v[8:9], v[2:3], 0 op_sel_hi:[1,0]
	v_pk_add_f32 v[2:3], v[0:1], 0 op_sel_hi:[1,0]
	v_cvt_pk_bf16_f32 v0, v4, v5
	v_cvt_pk_bf16_f32 v1, v6, v7
	s_nop 0
	v_cvt_pk_bf16_f32 v2, v2, v3
	v_cvt_pk_bf16_f32 v3, v8, v9
	global_store_dwordx4 v[12:13], v[0:3], off offset:256
	s_mul_i32 s46, s44, s89
	s_add_i32 s46, s46, s15
	s_cmpk_gt_i32 s46, 0x10f
	s_mov_b64 s[44:45], -1
	s_cbranch_scc1 .LBB0_997
	s_ashr_i32 s44, s46, 31
	s_lshr_b32 s44, s44, 29
	s_add_i32 s44, s46, s44
	s_ashr_i32 s45, s44, 3
	s_and_b32 s44, s44, -8
	s_sub_i32 s44, s46, s44
	s_cmp_lt_i32 s44, 0
	s_cselect_b32 s46, 35, 34
	s_mul_i32 s44, s46, s44
	s_add_i32 s44, s44, s45
	s_ashr_i32 s45, s44, 31
	s_lshr_b32 s45, s45, 26
	s_add_i32 s45, s44, s45
	s_ashr_i32 s46, s45, 6
	s_lshl_b32 s46, s46, 3
	s_sub_i32 s47, 34, s46
	s_min_u32 s47, s47, 8
	s_andn2_b32 s45, s45, 63
	s_sub_i32 s52, s44, s45
	v_cvt_f32_ubyte0_e32 v1, s47
	v_cvt_f32_i32_e32 v0, s52
	v_rcp_iflag_f32_e32 v2, v1
	s_ashr_i32 s44, s52, 30
	s_or_b32 s53, s44, 1
	v_mul_f32_e32 v2, v0, v2
	v_trunc_f32_e32 v2, v2
	v_fma_f32 v0, -v2, v1, v0
	v_cvt_i32_f32_e32 v2, v2
	v_cmp_ge_f32_e64 s[44:45], |v0|, v1
	s_and_b64 s[44:45], s[44:45], exec
	s_cselect_b32 s44, s53, 0
	v_readfirstlane_b32 s45, v2
	s_add_i32 s44, s45, s44
	s_sext_i32_i8 s69, s44
	s_mul_i32 s44, s44, s47
	s_sub_i32 s44, s52, s44
	s_sext_i32_i8 s44, s44
	s_add_i32 s68, s46, s44
	s_mov_b64 s[44:45], 0
	s_branch .LBB0_997

.LBB0_1007:
	s_add_u32 s8, s4, 0xac33600
	s_addc_u32 s9, s5, 0
	s_add_i32 s10, s13, s14
	s_add_i32 s11, s10, -16
	s_sub_i32 s10, 16, s10
	s_max_i32 s10, s11, s10
	s_mul_hi_u32 s1, s10, s1
	s_mul_i32 s1, s1, s0
	s_sub_i32 s1, s10, s1
	s_ashr_i32 s14, s11, 31
	s_sub_i32 s10, s1, s0
	s_cmp_ge_u32 s1, s0
	s_cselect_b32 s1, s10, s1
	s_sub_i32 s10, s1, s0
	s_cmp_ge_u32 s1, s0
	s_cselect_b32 s0, s10, s1
	s_xor_b32 s0, s0, s14
	s_sub_i32 s0, s0, s14
	v_mov_b32_e32 v4, v136
	s_cmp_lg_u32 s13, 0x100
	s_cbranch_scc1 .Lrb_dft_l1
	s_sub_i32 s0, s88, 128
	s_cmp_lt_u32 s88, 192
	s_cselect_b32 s0, -1, s0
	s_cmp_lt_u32 s88, 64
	s_cselect_b32 s0, s88, s0
.Lrb_dft_l1:
	s_cmpk_gt_u32 s0, 0x7f
	v_readfirstlane_b32 s1, v4
	s_cbranch_scc1 .LBB0_1031
	v_bfe_i32 v1, v4, 27, 1
	v_lshlrev_b32_e32 v0, 4, v4
	v_lshrrev_b32_e32 v1, 22, v1
	v_add_u32_e32 v1, v0, v1
	v_and_b32_e32 v1, 0xfffffc00, v1
	v_sub_u32_e32 v0, v0, v1
	v_lshrrev_b32_e32 v1, 4, v0
	v_bitop3_b32 v1, v1, v0, 32 bitop3:0x6c
	v_ashrrev_i32_e32 v0, 31, v0
	v_lshrrev_b32_e32 v0, 26, v0
	v_add_u32_e32 v0, v1, v0
	v_ashrrev_i32_e32 v5, 6, v0
	v_ashrrev_i32_e32 v0, 31, v4
	v_lshrrev_b32_e32 v0, 26, v0
	v_add_u32_e32 v0, v4, v0
	v_ashrrev_i32_e32 v6, 6, v0
	v_lshlrev_b32_e32 v0, 3, v6
	v_and_b32_e32 v0, -16, v0
	v_add_u32_e32 v0, v5, v0
	v_and_b32_e32 v2, 3, v5
	v_lshrrev_b32_e32 v3, 2, v0
	v_lshlrev_b32_e32 v7, 1, v0
	v_and_or_b32 v2, v0, 32, v2
	v_and_b32_e32 v3, 4, v3
	v_and_b32_e32 v7, 24, v7
	s_add_u32 s14, s4, 0x78cb600
	v_or3_b32 v2, v2, v3, v7
	v_lshrrev_b32_e32 v3, 6, v0
	s_addc_u32 s15, s5, 0
	v_lshl_add_u32 v2, v2, 6, v3
	s_movk_i32 s10, 0x2400
	s_lshl_b32 s11, s0, 4
	s_ashr_i32 s40, s1, 6
	v_mul_lo_u32 v2, v2, s10
	s_lshr_b32 s10, s0, 3
	s_and_b32 s11, s11, 0x70
	s_bfe_u32 s63, s0, 0x20003
	s_ashr_i32 s30, s1, 8
	s_lshl_b32 s31, s40, 10
	s_or_b32 s41, s11, s10
	s_lshl_b32 s10, s63, 18
	s_add_u32 s46, s14, s10
	v_mul_i32_i24_e32 v7, 64, v5
	s_addc_u32 s47, s15, 0
	s_lshl_b32 s10, s41, 6
	v_sub_u32_e32 v1, v1, v7
	v_mov_b32_e32 v7, 1
	s_and_b32 s10, s10, 0x1000
	s_and_b32 s11, s41, 60
	v_lshlrev_b32_e32 v3, 5, v6
	v_ashrrev_i16_sdwa v1, v7, sext(v1) dst_sel:DWORD dst_unused:UNUSED_PAD src0_sel:DWORD src1_sel:BYTE_0
	s_or_b32 s10, s10, s11
	v_and_b32_e32 v3, 32, v3
	v_bfe_i32 v7, v1, 0, 16
	s_mulk_i32 s10, 0x4800
	v_add_u32_e32 v1, v3, v7
	s_add_u32 s52, s8, s10
	v_mov_b32_e32 v133, 0
	v_add_lshl_u32 v128, v2, v1, 1
	v_lshlrev_b32_e32 v0, 10, v0
	s_addc_u32 s53, s9, 0
	v_mov_b32_e32 v129, v133
	s_add_i32 s33, s31, 0
	v_lshl_add_u32 v130, v1, 1, v0
	v_lshl_add_u64 v[0:1], s[52:53], 0, v[128:129]
	s_add_i32 m0, s33, 0x10000
	s_mov_b64 s[10:11], 0x4800
	global_load_lds_dwordx4 v128, s[52:53]
	v_lshl_add_u64 v[2:3], v[0:1], 0, s[10:11]
	s_add_i32 m0, s33, 0x12000
	v_mov_b32_e32 v131, v133
	global_load_lds_dwordx4 v[2:3], off
	v_lshl_add_u64 v[2:3], s[46:47], 0, v[130:131]
	s_mov_b32 m0, s33
	s_mov_b64 s[16:17], 0x10000
	s_add_i32 s48, s33, 0x2000
	global_load_lds_dwordx4 v130, s[46:47]
	v_lshl_add_u64 v[8:9], v[2:3], 0, s[16:17]
	s_mov_b32 m0, s48
	s_mov_b64 s[18:19], 0x9000
	global_load_lds_dwordx4 v[8:9], off
	v_lshl_add_u64 v[8:9], v[0:1], 0, s[18:19]
	s_add_i32 m0, s33, 0x14000
	s_mov_b64 s[20:21], 0xd800
	global_load_lds_dwordx4 v[8:9], off
	v_lshl_add_u64 v[8:9], v[0:1], 0, s[20:21]
	s_add_i32 m0, s33, 0x16000
	s_mov_b64 s[22:23], 0x20000
	s_add_i32 s49, s33, 0x4000
	global_load_lds_dwordx4 v[8:9], off
	v_lshl_add_u64 v[8:9], v[2:3], 0, s[22:23]
	s_mov_b32 m0, s49
	s_mov_b64 s[24:25], 0x30000
	s_add_i32 s50, s33, 0x6000
	global_load_lds_dwordx4 v[8:9], off
	v_lshl_add_u64 v[8:9], v[2:3], 0, s[24:25]
	s_mov_b32 m0, s50
	s_cmp_lg_u32 s30, 1
	global_load_lds_dwordx4 v[8:9], off
	s_mov_b32 s51, 0
	s_cbranch_scc1 .LBB0_1010
	s_barrier
